# FFN-down epilogue: LayerNorm-1 gain/bias quads loaded once per tile and kept in dead K-loop registers instead of 16 reloads behind the stores
# speedup vs baseline: 1.0149x; 1.0149x over previous
; DI float bperm(float v, int srclane) { return __int_as_float(__builtin_amdgcn_ds_bpermute(srclane << 2, __float_as_int(v))); }
; DI u32x4 pack8(const float (&v)[8]) { u32x4 w; w.x = pk2(v[0], v[1]); w.y = pk2(v[2], v[3]); w.z = pk2(v[4], v[5]); w.w = pk2(v[6], v[7]); return w; }
; DI void row_stats(const float* STAT, int row, int fq, int lane, float& mu, float& rstd) {
;     const f32x4 a = *(const f32x4*)(STAT + (size_t)row * 32 + fq * 8), b = *(const f32x4*)(STAT + (size_t)row * 32 + fq * 8 + 4);
;     float s = (a[0] + a[2]) + (b[0] + b[2]), q = (a[1] + a[3]) + (b[1] + b[3]);
;     s += bperm(s, lane ^ 16); q += bperm(q, lane ^ 16); s += bperm(s, lane ^ 32); q += bperm(q, lane ^ 32);
;     mu = s * (1.0f / 1024.0f); rstd = __builtin_amdgcn_rsqf(fmaxf(q * (1.0f / 1024.0f) - mu * mu, 0.f) + EPS);
;     DI void operator()(const f32x4 (&acc)[2][2][4][2], const pg8::Unit& u, int wr, int wc, int fr, int fq) const {
;     ...
;             for (int m = 0; m < 4; ++m) { const int row = row0 + ai * 128 + m * 16; const size_t off = (size_t)row * DMODEL + col0; float mu, rstd; row_stats(STAT, row, fq, lane, mu, rstd);
; #pragma unroll
;                 for (int bj = 0; bj < 2; ++bj) { float p[8]; unpack8(*(const u32x4*)(XBin + off + bj * 128), p);
;                     const f32x4 g0 = *(const f32x4*)(g + col0 + bj * 128), g1 = *(const f32x4*)(g + col0 + bj * 128 + 4), b0 = *(const f32x4*)(b + col0 + bj * 128), b1 = *(const f32x4*)(b + col0 + bj * 128 + 4);
;                     float o[8];
; #pragma unroll
;                     for (int k = 0; k < 8; ++k) { const float gg = k < 4 ? g0[k & 3] : g1[k & 3], bb = k < 4 ? b0[k & 3] : b1[k & 3]; const float x1 = (p[k] - mu) * rstd * gg + bb; o[k] = x1 * ALPHA + acc[ai][bj][m][k >> 2][k & 3]; }
;                     if (out32) { *(f32x4*)(out32 + off + bj * 128) = (f32x4){o[0], o[1], o[2], o[3]}; *(f32x4*)(out32 + off + bj * 128 + 4) = (f32x4){o[4], o[5], o[6], o[7]}; }
;                     else *(u32x4*)(XBout + off + bj * 128) = pack8(o); }
.LBB0_1979:
	s_lshl_b32 s2, s95, 8
	v_mov_b32_e32 v140, v159
	v_mov_b32_e32 v141, v158
	s_add_i32 s2, s2, s58
	s_andn2_b64 vcc, exec, s[44:45]
	v_add_u32_e32 v146, s2, v141
	s_lshl_b32 s2, s15, 8
	s_or_b32 s2, s2, s82
	v_lshlrev_b32_e32 v144, 3, v140
	v_lshlrev_b32_e32 v141, 2, v141
	v_add_u32_e32 v148, s2, v144
	v_lshl_add_u32 v140, v140, 6, v141
	v_ashrrev_i32_e32 v147, 31, v146
	v_ashrrev_i32_e32 v149, 31, v148
	v_xor_b32_e32 v163, 64, v140
	v_xor_b32_e32 v162, 0x80, v140
	v_lshlrev_b64 v[140:141], 10, v[146:147]
	v_lshl_add_u64 v[156:157], v[140:141], 0, v[148:149]
	v_lshlrev_b64 v[140:141], 7, v[146:147]
	v_ashrrev_i32_e32 v145, 31, v144
	v_lshl_add_u64 v[140:141], s[36:37], 0, v[140:141]
	v_lshl_add_u64 v[150:151], v[144:145], 2, v[140:141]
	global_load_dwordx4 v[140:143], v[150:151], off offset:16
	s_nop 0
	global_load_dwordx4 v[150:153], v[150:151], off
	s_mov_b32 s2, 0x3a800000
	v_cndmask_b32_e64 v147, 0, 1, s[44:45]
	v_cmp_ne_u32_e64 s[18:19], 1, v147
	s_waitcnt vmcnt(0)
	v_pk_add_f32 v[140:141], v[140:141], v[142:143]
	v_pk_add_f32 v[150:151], v[150:151], v[152:153]
	s_nop 0
	v_pk_add_f32 v[140:141], v[150:151], v[140:141]
	ds_bpermute_b32 v142, v163, v140
	ds_bpermute_b32 v143, v163, v141
	v_lshl_add_u64 v[150:151], v[156:157], 1, s[26:27]
	global_load_dwordx4 v[164:167], v[150:151], off
	v_lshl_add_u64 v[156:157], v[156:157], 2, s[28:29]
	s_waitcnt lgkmcnt(0)
	v_pk_add_f32 v[140:141], v[140:141], v[142:143]
	ds_bpermute_b32 v142, v162, v140
	ds_bpermute_b32 v143, v162, v141
	s_waitcnt lgkmcnt(0)
	v_pk_add_f32 v[140:141], v[140:141], v[142:143]
	s_nop 0
	v_pk_mul_f32 v[152:153], v[140:141], s[2:3] op_sel_hi:[1,0]
	s_waitcnt vmcnt(0)
	v_lshlrev_b32_e32 v184, 16, v164
	v_fma_f32 v140, -v152, v152, v153
	v_max_f32_e32 v140, 0, v140
	v_add_f32_e32 v140, 0x3727c5ac, v140
	v_rsq_f32_e32 v154, v140
	v_lshlrev_b64 v[140:141], 2, v[148:149]
	v_lshl_add_u64 v[142:143], s[20:21], 0, v[140:141]
	v_lshl_add_u64 v[140:141], s[22:23], 0, v[140:141]
	global_load_dwordx4 v[168:171], v[142:143], off offset:16
	global_load_dwordx4 v[172:175], v[142:143], off
	global_load_dwordx4 v[176:179], v[140:141], off offset:16
	global_load_dwordx4 v[180:183], v[140:141], off
	v_and_b32_e32 v185, 0xffff0000, v164
	v_lshlrev_b32_e32 v164, 16, v165
	v_and_b32_e32 v165, 0xffff0000, v165
	v_pk_add_f32 v[164:165], v[164:165], v[152:153] op_sel_hi:[1,0] neg_lo:[0,1] neg_hi:[0,1]
	v_pk_add_f32 v[184:185], v[184:185], v[152:153] op_sel_hi:[1,0] neg_lo:[0,1] neg_hi:[0,1]
	v_pk_mul_f32 v[164:165], v[164:165], v[154:155] op_sel_hi:[1,0]
	v_pk_mul_f32 v[184:185], v[184:185], v[154:155] op_sel_hi:[1,0]
	s_waitcnt vmcnt(0)
	v_mov_b32_e32 v220, v168
	v_mov_b32_e32 v221, v169
	v_mov_b32_e32 v222, v170
	v_mov_b32_e32 v223, v171
	v_mov_b32_e32 v224, v172
	v_mov_b32_e32 v225, v173
	v_mov_b32_e32 v226, v174
	v_mov_b32_e32 v227, v175
	v_mov_b32_e32 v228, v176
	v_mov_b32_e32 v229, v177
	v_mov_b32_e32 v230, v178
	v_mov_b32_e32 v231, v179
	v_mov_b32_e32 v232, v180
	v_mov_b32_e32 v233, v181
	v_mov_b32_e32 v234, v182
	v_mov_b32_e32 v235, v183
	v_pk_fma_f32 v[164:165], v[174:175], v[164:165], v[182:183]
	s_nop 0
	v_pk_fma_f32 v[128:129], v[164:165], s[86:87], v[128:129] op_sel_hi:[1,0,1]
	v_lshlrev_b32_e32 v164, 16, v166
	v_and_b32_e32 v165, 0xffff0000, v166
	v_pk_add_f32 v[164:165], v[164:165], v[152:153] op_sel_hi:[1,0] neg_lo:[0,1] neg_hi:[0,1]
	v_pk_fma_f32 v[172:173], v[172:173], v[184:185], v[180:181]
	v_pk_mul_f32 v[164:165], v[164:165], v[154:155] op_sel_hi:[1,0]
	v_pk_fma_f32 v[126:127], v[172:173], s[86:87], v[126:127] op_sel_hi:[1,0,1]
	v_pk_fma_f32 v[164:165], v[168:169], v[164:165], v[176:177]
	s_nop 0
	v_pk_fma_f32 v[122:123], v[164:165], s[86:87], v[122:123] op_sel_hi:[1,0,1]
	v_lshlrev_b32_e32 v164, 16, v167
	v_and_b32_e32 v165, 0xffff0000, v167
	v_pk_add_f32 v[164:165], v[164:165], v[152:153] op_sel_hi:[1,0] neg_lo:[0,1] neg_hi:[0,1]
	s_nop 0
	v_pk_mul_f32 v[164:165], v[164:165], v[154:155] op_sel_hi:[1,0]
	s_nop 0
	v_pk_fma_f32 v[164:165], v[170:171], v[164:165], v[178:179]
	s_nop 0
	v_pk_fma_f32 v[124:125], v[164:165], s[86:87], v[124:125] op_sel_hi:[1,0,1]
	s_cbranch_vccnz .LBB0_1981
	s_mov_b64 s[2:3], 0
	global_store_dwordx4 v[156:157], v[126:129], off
	global_store_dwordx4 v[156:157], v[122:125], off offset:16
	s_branch .LBB0_1982

; DI u32x4 pack8(const float (&v)[8]) { u32x4 w; w.x = pk2(v[0], v[1]); w.y = pk2(v[2], v[3]); w.z = pk2(v[4], v[5]); w.w = pk2(v[6], v[7]); return w; }
;     DI void operator()(const f32x4 (&acc)[2][2][4][2], const pg8::Unit& u, int wr, int wc, int fr, int fq) const {
;     ...
;                 for (int bj = 0; bj < 2; ++bj) { float p[8]; unpack8(*(const u32x4*)(XBin + off + bj * 128), p);
;                     const f32x4 g0 = *(const f32x4*)(g + col0 + bj * 128), g1 = *(const f32x4*)(g + col0 + bj * 128 + 4), b0 = *(const f32x4*)(b + col0 + bj * 128), b1 = *(const f32x4*)(b + col0 + bj * 128 + 4);
;                     float o[8];
; #pragma unroll
;                     for (int k = 0; k < 8; ++k) { const float gg = k < 4 ? g0[k & 3] : g1[k & 3], bb = k < 4 ? b0[k & 3] : b1[k & 3]; const float x1 = (p[k] - mu) * rstd * gg + bb; o[k] = x1 * ALPHA + acc[ai][bj][m][k >> 2][k & 3]; }
;                     if (out32) { *(f32x4*)(out32 + off + bj * 128) = (f32x4){o[0], o[1], o[2], o[3]}; *(f32x4*)(out32 + off + bj * 128 + 4) = (f32x4){o[4], o[5], o[6], o[7]}; }
;                     else *(u32x4*)(XBout + off + bj * 128) = pack8(o); }
.LBB0_1984:
	global_load_dwordx4 v[122:125], v[150:151], off offset:256
	s_nop 0
	global_load_dwordx4 v[126:129], v[142:143], off offset:528
	global_load_dwordx4 v[164:167], v[142:143], off offset:512
	global_load_dwordx4 v[168:171], v[140:141], off offset:528
	global_load_dwordx4 v[172:175], v[140:141], off offset:512
	v_mov_b32_e32 v153, v152
	v_mov_b32_e32 v155, v154
	s_and_b64 vcc, exec, s[18:19]
	s_waitcnt vmcnt(4)
	v_lshlrev_b32_e32 v176, 16, v122
	v_and_b32_e32 v177, 0xffff0000, v122
	v_lshlrev_b32_e32 v122, 16, v123
	v_and_b32_e32 v123, 0xffff0000, v123
	v_pk_add_f32 v[122:123], v[122:123], v[152:153] neg_lo:[0,1] neg_hi:[0,1]
	v_pk_add_f32 v[176:177], v[176:177], v[152:153] neg_lo:[0,1] neg_hi:[0,1]
	v_pk_mul_f32 v[122:123], v[154:155], v[122:123]
	v_pk_mul_f32 v[176:177], v[154:155], v[176:177]
	s_waitcnt vmcnt(0)
	v_mov_b32_e32 v242, v126
	v_mov_b32_e32 v243, v127
	v_mov_b32_e32 v244, v128
	v_mov_b32_e32 v245, v129
	v_mov_b32_e32 v246, v164
	v_mov_b32_e32 v247, v165
	v_mov_b32_e32 v248, v166
	v_mov_b32_e32 v249, v167
	v_mov_b32_e32 v250, v168
	v_mov_b32_e32 v251, v169
	v_mov_b32_e32 v252, v170
	v_mov_b32_e32 v253, v171
	v_mov_b32_e32 v186, v172
	v_mov_b32_e32 v187, v173
	v_mov_b32_e32 v196, v174
	v_mov_b32_e32 v197, v175
	v_pk_fma_f32 v[122:123], v[166:167], v[122:123], v[174:175]
	v_pk_fma_f32 v[164:165], v[164:165], v[176:177], v[172:173]
	v_pk_fma_f32 v[120:121], v[122:123], s[86:87], v[120:121] op_sel_hi:[1,0,1]
	v_lshlrev_b32_e32 v122, 16, v124
	v_and_b32_e32 v123, 0xffff0000, v124
	v_pk_add_f32 v[122:123], v[122:123], v[152:153] neg_lo:[0,1] neg_hi:[0,1]
	v_pk_fma_f32 v[118:119], v[164:165], s[86:87], v[118:119] op_sel_hi:[1,0,1]
	v_pk_mul_f32 v[122:123], v[154:155], v[122:123]
	s_nop 0
	v_pk_fma_f32 v[122:123], v[126:127], v[122:123], v[168:169]
	s_nop 0
	v_pk_fma_f32 v[114:115], v[122:123], s[86:87], v[114:115] op_sel_hi:[1,0,1]
	v_lshlrev_b32_e32 v122, 16, v125
	v_and_b32_e32 v123, 0xffff0000, v125
	v_pk_add_f32 v[122:123], v[122:123], v[152:153] neg_lo:[0,1] neg_hi:[0,1]
	s_nop 0
	v_pk_mul_f32 v[122:123], v[154:155], v[122:123]
	s_nop 0
	v_pk_fma_f32 v[122:123], v[128:129], v[122:123], v[170:171]
	s_nop 0
	v_pk_fma_f32 v[116:117], v[122:123], s[86:87], v[116:117] op_sel_hi:[1,0,1]
	s_cbranch_vccnz .LBB0_2032
	global_store_dwordx4 v[156:157], v[118:121], off offset:512
	global_store_dwordx4 v[156:157], v[114:117], off offset:528
	s_cbranch_execnz .LBB0_1987

; DI u32x4 pack8(const float (&v)[8]) { u32x4 w; w.x = pk2(v[0], v[1]); w.y = pk2(v[2], v[3]); w.z = pk2(v[4], v[5]); w.w = pk2(v[6], v[7]); return w; }
;     DI void operator()(const f32x4 (&acc)[2][2][4][2], const pg8::Unit& u, int wr, int wc, int fr, int fq) const {
;     ...
;             for (int m = 0; m < 4; ++m) { const int row = row0 + ai * 128 + m * 16; const size_t off = (size_t)row * DMODEL + col0; float mu, rstd; row_stats(STAT, row, fq, lane, mu, rstd);
; #pragma unroll
;                 for (int bj = 0; bj < 2; ++bj) { float p[8]; unpack8(*(const u32x4*)(XBin + off + bj * 128), p);
;                     const f32x4 g0 = *(const f32x4*)(g + col0 + bj * 128), g1 = *(const f32x4*)(g + col0 + bj * 128 + 4), b0 = *(const f32x4*)(b + col0 + bj * 128), b1 = *(const f32x4*)(b + col0 + bj * 128 + 4);
;                     float o[8];
; #pragma unroll
;                     for (int k = 0; k < 8; ++k) { const float gg = k < 4 ? g0[k & 3] : g1[k & 3], bb = k < 4 ? b0[k & 3] : b1[k & 3]; const float x1 = (p[k] - mu) * rstd * gg + bb; o[k] = x1 * ALPHA + acc[ai][bj][m][k >> 2][k & 3]; }
;                     if (out32) { *(f32x4*)(out32 + off + bj * 128) = (f32x4){o[0], o[1], o[2], o[3]}; *(f32x4*)(out32 + off + bj * 128 + 4) = (f32x4){o[4], o[5], o[6], o[7]}; }
;                     else *(u32x4*)(XBout + off + bj * 128) = pack8(o); }
.LBB0_1987:
	s_nop 0
	v_add_u32_e32 v114, 16, v146
	v_ashrrev_i32_e32 v115, 31, v114
	v_lshlrev_b64 v[116:117], 10, v[114:115]
	v_lshlrev_b64 v[114:115], 7, v[114:115]
	v_lshl_add_u64 v[114:115], s[36:37], 0, v[114:115]
	v_lshl_add_u64 v[118:119], v[144:145], 2, v[114:115]
	s_nop 1
	v_mov_b32_e32 v122, v220
	v_mov_b32_e32 v123, v221
	v_mov_b32_e32 v124, v222
	v_mov_b32_e32 v125, v223
	v_mov_b32_e32 v126, v224
	v_mov_b32_e32 v127, v225
	v_mov_b32_e32 v128, v226
	v_mov_b32_e32 v129, v227
	v_mov_b32_e32 v150, v228
	v_mov_b32_e32 v151, v229
	v_mov_b32_e32 v152, v230
	v_mov_b32_e32 v153, v231
	v_mov_b32_e32 v154, v232
	v_mov_b32_e32 v155, v233
	v_mov_b32_e32 v156, v234
	v_mov_b32_e32 v157, v235
	v_lshl_add_u64 v[120:121], v[116:117], 0, v[148:149]
	global_load_dwordx4 v[114:117], v[118:119], off offset:16
	global_load_dwordx4 v[164:167], v[118:119], off
	s_mov_b32 s2, 0x3a800000
	s_and_b64 vcc, exec, s[18:19]
	s_waitcnt vmcnt(1)
	v_pk_add_f32 v[114:115], v[114:115], v[116:117]
	s_waitcnt vmcnt(0)
	v_pk_add_f32 v[118:119], v[164:165], v[166:167]
	s_nop 0
	v_pk_add_f32 v[114:115], v[118:119], v[114:115]
	ds_bpermute_b32 v116, v163, v114
	ds_bpermute_b32 v117, v163, v115
	s_waitcnt lgkmcnt(0)
	v_pk_add_f32 v[114:115], v[114:115], v[116:117]
	ds_bpermute_b32 v116, v162, v114
	ds_bpermute_b32 v117, v162, v115
	s_waitcnt lgkmcnt(0)
	v_pk_add_f32 v[114:115], v[114:115], v[116:117]
	s_nop 0
	v_pk_mul_f32 v[116:117], v[114:115], s[2:3] op_sel_hi:[1,0]
	s_nop 0
	v_fma_f32 v114, -v116, v116, v117
	v_max_f32_e32 v114, 0, v114
	v_add_f32_e32 v114, 0x3727c5ac, v114
	v_rsq_f32_e32 v118, v114
	v_lshl_add_u64 v[114:115], v[120:121], 1, s[26:27]
	global_load_dwordx4 v[164:167], v[114:115], off
	v_lshl_add_u64 v[120:121], v[120:121], 2, s[28:29]
	s_waitcnt vmcnt(0)
	v_lshlrev_b32_e32 v168, 16, v164
	v_and_b32_e32 v169, 0xffff0000, v164
	v_pk_add_f32 v[168:169], v[168:169], v[116:117] op_sel_hi:[1,0] neg_lo:[0,1] neg_hi:[0,1]
	s_nop 0
	v_pk_mul_f32 v[168:169], v[168:169], v[118:119] op_sel_hi:[1,0]
	s_nop 0
	v_pk_fma_f32 v[126:127], v[126:127], v[168:169], v[154:155]
	s_nop 0
	v_pk_fma_f32 v[110:111], v[126:127], s[86:87], v[110:111] op_sel_hi:[1,0,1]
	v_lshlrev_b32_e32 v126, 16, v165
	v_and_b32_e32 v127, 0xffff0000, v165
	v_pk_add_f32 v[126:127], v[126:127], v[116:117] op_sel_hi:[1,0] neg_lo:[0,1] neg_hi:[0,1]
	s_nop 0
	v_pk_mul_f32 v[126:127], v[126:127], v[118:119] op_sel_hi:[1,0]
	s_nop 0
	v_pk_fma_f32 v[126:127], v[128:129], v[126:127], v[156:157]
	s_nop 0
	v_pk_fma_f32 v[112:113], v[126:127], s[86:87], v[112:113] op_sel_hi:[1,0,1]
	v_lshlrev_b32_e32 v126, 16, v166
	v_and_b32_e32 v127, 0xffff0000, v166
	v_pk_add_f32 v[126:127], v[126:127], v[116:117] op_sel_hi:[1,0] neg_lo:[0,1] neg_hi:[0,1]
	s_nop 0
	v_pk_mul_f32 v[126:127], v[126:127], v[118:119] op_sel_hi:[1,0]
	s_nop 0
	v_pk_fma_f32 v[122:123], v[122:123], v[126:127], v[150:151]
	s_nop 0
	v_pk_fma_f32 v[106:107], v[122:123], s[86:87], v[106:107] op_sel_hi:[1,0,1]
	v_lshlrev_b32_e32 v122, 16, v167
	v_and_b32_e32 v123, 0xffff0000, v167
	v_pk_add_f32 v[122:123], v[122:123], v[116:117] op_sel_hi:[1,0] neg_lo:[0,1] neg_hi:[0,1]
	s_nop 0
	v_pk_mul_f32 v[122:123], v[122:123], v[118:119] op_sel_hi:[1,0]
	s_nop 0
	v_pk_fma_f32 v[122:123], v[124:125], v[122:123], v[152:153]
	s_nop 0
	v_pk_fma_f32 v[108:109], v[122:123], s[86:87], v[108:109] op_sel_hi:[1,0,1]
	s_cbranch_vccnz .LBB0_2033
	global_store_dwordx4 v[120:121], v[110:113], off
	global_store_dwordx4 v[120:121], v[106:109], off offset:16
	s_cbranch_execnz .LBB0_1990

; DI u32x4 pack8(const float (&v)[8]) { u32x4 w; w.x = pk2(v[0], v[1]); w.y = pk2(v[2], v[3]); w.z = pk2(v[4], v[5]); w.w = pk2(v[6], v[7]); return w; }
;     DI void operator()(const f32x4 (&acc)[2][2][4][2], const pg8::Unit& u, int wr, int wc, int fr, int fq) const {
;     ...
;                 for (int bj = 0; bj < 2; ++bj) { float p[8]; unpack8(*(const u32x4*)(XBin + off + bj * 128), p);
;                     const f32x4 g0 = *(const f32x4*)(g + col0 + bj * 128), g1 = *(const f32x4*)(g + col0 + bj * 128 + 4), b0 = *(const f32x4*)(b + col0 + bj * 128), b1 = *(const f32x4*)(b + col0 + bj * 128 + 4);
;                     float o[8];
; #pragma unroll
;                     for (int k = 0; k < 8; ++k) { const float gg = k < 4 ? g0[k & 3] : g1[k & 3], bb = k < 4 ? b0[k & 3] : b1[k & 3]; const float x1 = (p[k] - mu) * rstd * gg + bb; o[k] = x1 * ALPHA + acc[ai][bj][m][k >> 2][k & 3]; }
;                     if (out32) { *(f32x4*)(out32 + off + bj * 128) = (f32x4){o[0], o[1], o[2], o[3]}; *(f32x4*)(out32 + off + bj * 128 + 4) = (f32x4){o[4], o[5], o[6], o[7]}; }
;                     else *(u32x4*)(XBout + off + bj * 128) = pack8(o); }
.LBB0_1990:
	global_load_dwordx4 v[106:109], v[114:115], off offset:256
	s_nop 0
	s_nop 1
	v_mov_b32_e32 v110, v242
	v_mov_b32_e32 v111, v243
	v_mov_b32_e32 v112, v244
	v_mov_b32_e32 v113, v245
	v_mov_b32_e32 v122, v246
	v_mov_b32_e32 v123, v247
	v_mov_b32_e32 v124, v248
	v_mov_b32_e32 v125, v249
	v_mov_b32_e32 v126, v250
	v_mov_b32_e32 v127, v251
	v_mov_b32_e32 v128, v252
	v_mov_b32_e32 v129, v253
	v_mov_b32_e32 v150, v186
	v_mov_b32_e32 v151, v187
	v_mov_b32_e32 v152, v196
	v_mov_b32_e32 v153, v197
	v_mov_b32_e32 v117, v116
	v_mov_b32_e32 v119, v118
	s_and_b64 vcc, exec, s[18:19]
	s_waitcnt vmcnt(0)
	v_lshlrev_b32_e32 v154, 16, v106
	v_and_b32_e32 v155, 0xffff0000, v106
	v_lshlrev_b32_e32 v106, 16, v107
	v_and_b32_e32 v107, 0xffff0000, v107
	v_pk_add_f32 v[106:107], v[106:107], v[116:117] neg_lo:[0,1] neg_hi:[0,1]
	v_pk_add_f32 v[154:155], v[154:155], v[116:117] neg_lo:[0,1] neg_hi:[0,1]
	v_pk_mul_f32 v[106:107], v[118:119], v[106:107]
	v_pk_mul_f32 v[154:155], v[118:119], v[154:155]
	s_waitcnt vmcnt(0)
	v_pk_fma_f32 v[106:107], v[124:125], v[106:107], v[152:153]
	v_pk_fma_f32 v[122:123], v[122:123], v[154:155], v[150:151]
	v_pk_fma_f32 v[104:105], v[106:107], s[86:87], v[104:105] op_sel_hi:[1,0,1]
	v_lshlrev_b32_e32 v106, 16, v108
	v_and_b32_e32 v107, 0xffff0000, v108
	v_pk_add_f32 v[106:107], v[106:107], v[116:117] neg_lo:[0,1] neg_hi:[0,1]
	v_pk_fma_f32 v[102:103], v[122:123], s[86:87], v[102:103] op_sel_hi:[1,0,1]
	v_pk_mul_f32 v[106:107], v[118:119], v[106:107]
	s_nop 0
	v_pk_fma_f32 v[106:107], v[110:111], v[106:107], v[126:127]
	s_nop 0
	v_pk_fma_f32 v[98:99], v[106:107], s[86:87], v[98:99] op_sel_hi:[1,0,1]
	v_lshlrev_b32_e32 v106, 16, v109
	v_and_b32_e32 v107, 0xffff0000, v109
	v_pk_add_f32 v[106:107], v[106:107], v[116:117] neg_lo:[0,1] neg_hi:[0,1]
	s_nop 0
	v_pk_mul_f32 v[106:107], v[118:119], v[106:107]
	s_nop 0
	v_pk_fma_f32 v[106:107], v[112:113], v[106:107], v[128:129]
	s_nop 0
	v_pk_fma_f32 v[100:101], v[106:107], s[86:87], v[100:101] op_sel_hi:[1,0,1]
	s_cbranch_vccnz .LBB0_2034
	global_store_dwordx4 v[120:121], v[102:105], off offset:512
	global_store_dwordx4 v[120:121], v[98:101], off offset:528
	s_cbranch_execnz .LBB0_1993

; DI u32x4 pack8(const float (&v)[8]) { u32x4 w; w.x = pk2(v[0], v[1]); w.y = pk2(v[2], v[3]); w.z = pk2(v[4], v[5]); w.w = pk2(v[6], v[7]); return w; }
;     DI void operator()(const f32x4 (&acc)[2][2][4][2], const pg8::Unit& u, int wr, int wc, int fr, int fq) const {
;     ...
;             for (int m = 0; m < 4; ++m) { const int row = row0 + ai * 128 + m * 16; const size_t off = (size_t)row * DMODEL + col0; float mu, rstd; row_stats(STAT, row, fq, lane, mu, rstd);
; #pragma unroll
;                 for (int bj = 0; bj < 2; ++bj) { float p[8]; unpack8(*(const u32x4*)(XBin + off + bj * 128), p);
;                     const f32x4 g0 = *(const f32x4*)(g + col0 + bj * 128), g1 = *(const f32x4*)(g + col0 + bj * 128 + 4), b0 = *(const f32x4*)(b + col0 + bj * 128), b1 = *(const f32x4*)(b + col0 + bj * 128 + 4);
;                     float o[8];
; #pragma unroll
;                     for (int k = 0; k < 8; ++k) { const float gg = k < 4 ? g0[k & 3] : g1[k & 3], bb = k < 4 ? b0[k & 3] : b1[k & 3]; const float x1 = (p[k] - mu) * rstd * gg + bb; o[k] = x1 * ALPHA + acc[ai][bj][m][k >> 2][k & 3]; }
;                     if (out32) { *(f32x4*)(out32 + off + bj * 128) = (f32x4){o[0], o[1], o[2], o[3]}; *(f32x4*)(out32 + off + bj * 128 + 4) = (f32x4){o[4], o[5], o[6], o[7]}; }
;                     else *(u32x4*)(XBout + off + bj * 128) = pack8(o); }
.LBB0_1993:
	s_nop 0
	v_add_u32_e32 v98, 32, v146
	v_ashrrev_i32_e32 v99, 31, v98
	v_lshlrev_b64 v[100:101], 10, v[98:99]
	v_lshlrev_b64 v[98:99], 7, v[98:99]
	v_lshl_add_u64 v[98:99], s[36:37], 0, v[98:99]
	v_lshl_add_u64 v[102:103], v[144:145], 2, v[98:99]
	s_nop 1
	v_mov_b32_e32 v106, v220
	v_mov_b32_e32 v107, v221
	v_mov_b32_e32 v108, v222
	v_mov_b32_e32 v109, v223
	v_mov_b32_e32 v110, v224
	v_mov_b32_e32 v111, v225
	v_mov_b32_e32 v112, v226
	v_mov_b32_e32 v113, v227
	v_mov_b32_e32 v114, v228
	v_mov_b32_e32 v115, v229
	v_mov_b32_e32 v116, v230
	v_mov_b32_e32 v117, v231
	v_mov_b32_e32 v118, v232
	v_mov_b32_e32 v119, v233
	v_mov_b32_e32 v120, v234
	v_mov_b32_e32 v121, v235
	v_lshl_add_u64 v[104:105], v[100:101], 0, v[148:149]
	global_load_dwordx4 v[98:101], v[102:103], off offset:16
	global_load_dwordx4 v[122:125], v[102:103], off
	s_mov_b32 s2, 0x3a800000
	s_and_b64 vcc, exec, s[18:19]
	s_waitcnt vmcnt(1)
	v_pk_add_f32 v[98:99], v[98:99], v[100:101]
	s_waitcnt vmcnt(0)
	v_pk_add_f32 v[102:103], v[122:123], v[124:125]
	s_nop 0
	v_pk_add_f32 v[98:99], v[102:103], v[98:99]
	ds_bpermute_b32 v100, v163, v98
	ds_bpermute_b32 v101, v163, v99
	s_waitcnt lgkmcnt(0)
	v_pk_add_f32 v[98:99], v[98:99], v[100:101]
	ds_bpermute_b32 v100, v162, v98
	ds_bpermute_b32 v101, v162, v99
	s_waitcnt lgkmcnt(0)
	v_pk_add_f32 v[98:99], v[98:99], v[100:101]
	s_nop 0
	v_pk_mul_f32 v[100:101], v[98:99], s[2:3] op_sel_hi:[1,0]
	s_nop 0
	v_fma_f32 v98, -v100, v100, v101
	v_max_f32_e32 v98, 0, v98
	v_add_f32_e32 v98, 0x3727c5ac, v98
	v_rsq_f32_e32 v102, v98
	v_lshl_add_u64 v[98:99], v[104:105], 1, s[26:27]
	global_load_dwordx4 v[122:125], v[98:99], off
	v_lshl_add_u64 v[104:105], v[104:105], 2, s[28:29]
	s_waitcnt vmcnt(0)
	v_lshlrev_b32_e32 v126, 16, v122
	v_and_b32_e32 v127, 0xffff0000, v122
	v_pk_add_f32 v[126:127], v[126:127], v[100:101] op_sel_hi:[1,0] neg_lo:[0,1] neg_hi:[0,1]
	s_nop 0
	v_pk_mul_f32 v[126:127], v[126:127], v[102:103] op_sel_hi:[1,0]
	s_nop 0
	v_pk_fma_f32 v[110:111], v[110:111], v[126:127], v[118:119]
	s_nop 0
	v_pk_fma_f32 v[94:95], v[110:111], s[86:87], v[94:95] op_sel_hi:[1,0,1]
	v_lshlrev_b32_e32 v110, 16, v123
	v_and_b32_e32 v111, 0xffff0000, v123
	v_pk_add_f32 v[110:111], v[110:111], v[100:101] op_sel_hi:[1,0] neg_lo:[0,1] neg_hi:[0,1]
	s_nop 0
	v_pk_mul_f32 v[110:111], v[110:111], v[102:103] op_sel_hi:[1,0]
	s_nop 0
	v_pk_fma_f32 v[110:111], v[112:113], v[110:111], v[120:121]
	s_nop 0
	v_pk_fma_f32 v[96:97], v[110:111], s[86:87], v[96:97] op_sel_hi:[1,0,1]
	v_lshlrev_b32_e32 v110, 16, v124
	v_and_b32_e32 v111, 0xffff0000, v124
	v_pk_add_f32 v[110:111], v[110:111], v[100:101] op_sel_hi:[1,0] neg_lo:[0,1] neg_hi:[0,1]
	s_nop 0
	v_pk_mul_f32 v[110:111], v[110:111], v[102:103] op_sel_hi:[1,0]
	s_nop 0
	v_pk_fma_f32 v[106:107], v[106:107], v[110:111], v[114:115]
	s_nop 0
	v_pk_fma_f32 v[90:91], v[106:107], s[86:87], v[90:91] op_sel_hi:[1,0,1]
	v_lshlrev_b32_e32 v106, 16, v125
	v_and_b32_e32 v107, 0xffff0000, v125
	v_pk_add_f32 v[106:107], v[106:107], v[100:101] op_sel_hi:[1,0] neg_lo:[0,1] neg_hi:[0,1]
	s_nop 0
	v_pk_mul_f32 v[106:107], v[106:107], v[102:103] op_sel_hi:[1,0]
	s_nop 0
	v_pk_fma_f32 v[106:107], v[108:109], v[106:107], v[116:117]
	s_nop 0
	v_pk_fma_f32 v[92:93], v[106:107], s[86:87], v[92:93] op_sel_hi:[1,0,1]
	s_cbranch_vccnz .LBB0_2035
	global_store_dwordx4 v[104:105], v[94:97], off
	global_store_dwordx4 v[104:105], v[90:93], off offset:16
	s_cbranch_execnz .LBB0_1996

; DI u32x4 pack8(const float (&v)[8]) { u32x4 w; w.x = pk2(v[0], v[1]); w.y = pk2(v[2], v[3]); w.z = pk2(v[4], v[5]); w.w = pk2(v[6], v[7]); return w; }
;     DI void operator()(const f32x4 (&acc)[2][2][4][2], const pg8::Unit& u, int wr, int wc, int fr, int fq) const {
;     ...
;                 for (int bj = 0; bj < 2; ++bj) { float p[8]; unpack8(*(const u32x4*)(XBin + off + bj * 128), p);
;                     const f32x4 g0 = *(const f32x4*)(g + col0 + bj * 128), g1 = *(const f32x4*)(g + col0 + bj * 128 + 4), b0 = *(const f32x4*)(b + col0 + bj * 128), b1 = *(const f32x4*)(b + col0 + bj * 128 + 4);
;                     float o[8];
; #pragma unroll
;                     for (int k = 0; k < 8; ++k) { const float gg = k < 4 ? g0[k & 3] : g1[k & 3], bb = k < 4 ? b0[k & 3] : b1[k & 3]; const float x1 = (p[k] - mu) * rstd * gg + bb; o[k] = x1 * ALPHA + acc[ai][bj][m][k >> 2][k & 3]; }
;                     if (out32) { *(f32x4*)(out32 + off + bj * 128) = (f32x4){o[0], o[1], o[2], o[3]}; *(f32x4*)(out32 + off + bj * 128 + 4) = (f32x4){o[4], o[5], o[6], o[7]}; }
;                     else *(u32x4*)(XBout + off + bj * 128) = pack8(o); }
.LBB0_1996:
	global_load_dwordx4 v[90:93], v[98:99], off offset:256
	s_nop 0
	s_nop 1
	v_mov_b32_e32 v94, v242
	v_mov_b32_e32 v95, v243
	v_mov_b32_e32 v96, v244
	v_mov_b32_e32 v97, v245
	v_mov_b32_e32 v106, v246
	v_mov_b32_e32 v107, v247
	v_mov_b32_e32 v108, v248
	v_mov_b32_e32 v109, v249
	v_mov_b32_e32 v110, v250
	v_mov_b32_e32 v111, v251
	v_mov_b32_e32 v112, v252
	v_mov_b32_e32 v113, v253
	v_mov_b32_e32 v114, v186
	v_mov_b32_e32 v115, v187
	v_mov_b32_e32 v116, v196
	v_mov_b32_e32 v117, v197
	v_mov_b32_e32 v101, v100
	v_mov_b32_e32 v103, v102
	s_and_b64 vcc, exec, s[18:19]
	s_waitcnt vmcnt(0)
	v_lshlrev_b32_e32 v118, 16, v90
	v_and_b32_e32 v119, 0xffff0000, v90
	v_lshlrev_b32_e32 v90, 16, v91
	v_and_b32_e32 v91, 0xffff0000, v91
	v_pk_add_f32 v[90:91], v[90:91], v[100:101] neg_lo:[0,1] neg_hi:[0,1]
	v_pk_add_f32 v[118:119], v[118:119], v[100:101] neg_lo:[0,1] neg_hi:[0,1]
	v_pk_mul_f32 v[90:91], v[102:103], v[90:91]
	v_pk_mul_f32 v[118:119], v[102:103], v[118:119]
	s_waitcnt vmcnt(0)
	v_pk_fma_f32 v[90:91], v[108:109], v[90:91], v[116:117]
	v_pk_fma_f32 v[106:107], v[106:107], v[118:119], v[114:115]
	v_pk_fma_f32 v[88:89], v[90:91], s[86:87], v[88:89] op_sel_hi:[1,0,1]
	v_lshlrev_b32_e32 v90, 16, v92
	v_and_b32_e32 v91, 0xffff0000, v92
	v_pk_add_f32 v[90:91], v[90:91], v[100:101] neg_lo:[0,1] neg_hi:[0,1]
	v_pk_fma_f32 v[86:87], v[106:107], s[86:87], v[86:87] op_sel_hi:[1,0,1]
	v_pk_mul_f32 v[90:91], v[102:103], v[90:91]
	s_nop 0
	v_pk_fma_f32 v[90:91], v[94:95], v[90:91], v[110:111]
	s_nop 0
	v_pk_fma_f32 v[82:83], v[90:91], s[86:87], v[82:83] op_sel_hi:[1,0,1]
	v_lshlrev_b32_e32 v90, 16, v93
	v_and_b32_e32 v91, 0xffff0000, v93
	v_pk_add_f32 v[90:91], v[90:91], v[100:101] neg_lo:[0,1] neg_hi:[0,1]
	s_nop 0
	v_pk_mul_f32 v[90:91], v[102:103], v[90:91]
	s_nop 0
	v_pk_fma_f32 v[90:91], v[96:97], v[90:91], v[112:113]
	s_nop 0
	v_pk_fma_f32 v[84:85], v[90:91], s[86:87], v[84:85] op_sel_hi:[1,0,1]
	s_cbranch_vccnz .LBB0_2036
	global_store_dwordx4 v[104:105], v[86:89], off offset:512
	global_store_dwordx4 v[104:105], v[82:85], off offset:528
	s_cbranch_execnz .LBB0_1999

; DI u32x4 pack8(const float (&v)[8]) { u32x4 w; w.x = pk2(v[0], v[1]); w.y = pk2(v[2], v[3]); w.z = pk2(v[4], v[5]); w.w = pk2(v[6], v[7]); return w; }
;     DI void operator()(const f32x4 (&acc)[2][2][4][2], const pg8::Unit& u, int wr, int wc, int fr, int fq) const {
;     ...
;             for (int m = 0; m < 4; ++m) { const int row = row0 + ai * 128 + m * 16; const size_t off = (size_t)row * DMODEL + col0; float mu, rstd; row_stats(STAT, row, fq, lane, mu, rstd);
; #pragma unroll
;                 for (int bj = 0; bj < 2; ++bj) { float p[8]; unpack8(*(const u32x4*)(XBin + off + bj * 128), p);
;                     const f32x4 g0 = *(const f32x4*)(g + col0 + bj * 128), g1 = *(const f32x4*)(g + col0 + bj * 128 + 4), b0 = *(const f32x4*)(b + col0 + bj * 128), b1 = *(const f32x4*)(b + col0 + bj * 128 + 4);
;                     float o[8];
; #pragma unroll
;                     for (int k = 0; k < 8; ++k) { const float gg = k < 4 ? g0[k & 3] : g1[k & 3], bb = k < 4 ? b0[k & 3] : b1[k & 3]; const float x1 = (p[k] - mu) * rstd * gg + bb; o[k] = x1 * ALPHA + acc[ai][bj][m][k >> 2][k & 3]; }
;                     if (out32) { *(f32x4*)(out32 + off + bj * 128) = (f32x4){o[0], o[1], o[2], o[3]}; *(f32x4*)(out32 + off + bj * 128 + 4) = (f32x4){o[4], o[5], o[6], o[7]}; }
;                     else *(u32x4*)(XBout + off + bj * 128) = pack8(o); }
.LBB0_1999:
	s_nop 0
	v_add_u32_e32 v82, 48, v146
	v_ashrrev_i32_e32 v83, 31, v82
	v_lshlrev_b64 v[84:85], 10, v[82:83]
	v_lshlrev_b64 v[82:83], 7, v[82:83]
	v_lshl_add_u64 v[82:83], s[36:37], 0, v[82:83]
	v_lshl_add_u64 v[86:87], v[144:145], 2, v[82:83]
	s_nop 1
	v_mov_b32_e32 v90, v220
	v_mov_b32_e32 v91, v221
	v_mov_b32_e32 v92, v222
	v_mov_b32_e32 v93, v223
	v_mov_b32_e32 v94, v224
	v_mov_b32_e32 v95, v225
	v_mov_b32_e32 v96, v226
	v_mov_b32_e32 v97, v227
	v_mov_b32_e32 v98, v228
	v_mov_b32_e32 v99, v229
	v_mov_b32_e32 v100, v230
	v_mov_b32_e32 v101, v231
	v_mov_b32_e32 v102, v232
	v_mov_b32_e32 v103, v233
	v_mov_b32_e32 v104, v234
	v_mov_b32_e32 v105, v235
	v_lshl_add_u64 v[88:89], v[84:85], 0, v[148:149]
	global_load_dwordx4 v[82:85], v[86:87], off offset:16
	global_load_dwordx4 v[106:109], v[86:87], off
	s_mov_b32 s2, 0x3a800000
	s_and_b64 vcc, exec, s[18:19]
	s_waitcnt vmcnt(1)
	v_pk_add_f32 v[82:83], v[82:83], v[84:85]
	s_waitcnt vmcnt(0)
	v_pk_add_f32 v[86:87], v[106:107], v[108:109]
	s_nop 0
	v_pk_add_f32 v[82:83], v[86:87], v[82:83]
	ds_bpermute_b32 v84, v163, v82
	ds_bpermute_b32 v85, v163, v83
	s_waitcnt lgkmcnt(0)
	v_pk_add_f32 v[82:83], v[82:83], v[84:85]
	ds_bpermute_b32 v84, v162, v82
	ds_bpermute_b32 v85, v162, v83
	s_waitcnt lgkmcnt(0)
	v_pk_add_f32 v[82:83], v[82:83], v[84:85]
	s_nop 0
	v_pk_mul_f32 v[84:85], v[82:83], s[2:3] op_sel_hi:[1,0]
	s_nop 0
	v_fma_f32 v82, -v84, v84, v85
	v_max_f32_e32 v82, 0, v82
	v_add_f32_e32 v82, 0x3727c5ac, v82
	v_rsq_f32_e32 v86, v82
	v_lshl_add_u64 v[82:83], v[88:89], 1, s[26:27]
	global_load_dwordx4 v[106:109], v[82:83], off
	v_lshl_add_u64 v[88:89], v[88:89], 2, s[28:29]
	s_waitcnt vmcnt(0)
	v_lshlrev_b32_e32 v110, 16, v106
	v_and_b32_e32 v111, 0xffff0000, v106
	v_pk_add_f32 v[110:111], v[110:111], v[84:85] op_sel_hi:[1,0] neg_lo:[0,1] neg_hi:[0,1]
	s_nop 0
	v_pk_mul_f32 v[110:111], v[110:111], v[86:87] op_sel_hi:[1,0]
	s_nop 0
	v_pk_fma_f32 v[94:95], v[94:95], v[110:111], v[102:103]
	s_nop 0
	v_pk_fma_f32 v[78:79], v[94:95], s[86:87], v[78:79] op_sel_hi:[1,0,1]
	v_lshlrev_b32_e32 v94, 16, v107
	v_and_b32_e32 v95, 0xffff0000, v107
	v_pk_add_f32 v[94:95], v[94:95], v[84:85] op_sel_hi:[1,0] neg_lo:[0,1] neg_hi:[0,1]
	s_nop 0
	v_pk_mul_f32 v[94:95], v[94:95], v[86:87] op_sel_hi:[1,0]
	s_nop 0
	v_pk_fma_f32 v[94:95], v[96:97], v[94:95], v[104:105]
	s_nop 0
	v_pk_fma_f32 v[80:81], v[94:95], s[86:87], v[80:81] op_sel_hi:[1,0,1]
	v_lshlrev_b32_e32 v94, 16, v108
	v_and_b32_e32 v95, 0xffff0000, v108
	v_pk_add_f32 v[94:95], v[94:95], v[84:85] op_sel_hi:[1,0] neg_lo:[0,1] neg_hi:[0,1]
	s_nop 0
	v_pk_mul_f32 v[94:95], v[94:95], v[86:87] op_sel_hi:[1,0]
	s_nop 0
	v_pk_fma_f32 v[90:91], v[90:91], v[94:95], v[98:99]
	s_nop 0
	v_pk_fma_f32 v[74:75], v[90:91], s[86:87], v[74:75] op_sel_hi:[1,0,1]
	v_lshlrev_b32_e32 v90, 16, v109
	v_and_b32_e32 v91, 0xffff0000, v109
	v_pk_add_f32 v[90:91], v[90:91], v[84:85] op_sel_hi:[1,0] neg_lo:[0,1] neg_hi:[0,1]
	s_nop 0
	v_pk_mul_f32 v[90:91], v[90:91], v[86:87] op_sel_hi:[1,0]
	s_nop 0
	v_pk_fma_f32 v[90:91], v[92:93], v[90:91], v[100:101]
	s_nop 0
	v_pk_fma_f32 v[76:77], v[90:91], s[86:87], v[76:77] op_sel_hi:[1,0,1]
	s_cbranch_vccnz .LBB0_2037
	global_store_dwordx4 v[88:89], v[78:81], off
	global_store_dwordx4 v[88:89], v[74:77], off offset:16
	s_cbranch_execnz .LBB0_2002

; DI u32x4 pack8(const float (&v)[8]) { u32x4 w; w.x = pk2(v[0], v[1]); w.y = pk2(v[2], v[3]); w.z = pk2(v[4], v[5]); w.w = pk2(v[6], v[7]); return w; }
;     DI void operator()(const f32x4 (&acc)[2][2][4][2], const pg8::Unit& u, int wr, int wc, int fr, int fq) const {
;     ...
;                 for (int bj = 0; bj < 2; ++bj) { float p[8]; unpack8(*(const u32x4*)(XBin + off + bj * 128), p);
;                     const f32x4 g0 = *(const f32x4*)(g + col0 + bj * 128), g1 = *(const f32x4*)(g + col0 + bj * 128 + 4), b0 = *(const f32x4*)(b + col0 + bj * 128), b1 = *(const f32x4*)(b + col0 + bj * 128 + 4);
;                     float o[8];
; #pragma unroll
;                     for (int k = 0; k < 8; ++k) { const float gg = k < 4 ? g0[k & 3] : g1[k & 3], bb = k < 4 ? b0[k & 3] : b1[k & 3]; const float x1 = (p[k] - mu) * rstd * gg + bb; o[k] = x1 * ALPHA + acc[ai][bj][m][k >> 2][k & 3]; }
;                     if (out32) { *(f32x4*)(out32 + off + bj * 128) = (f32x4){o[0], o[1], o[2], o[3]}; *(f32x4*)(out32 + off + bj * 128 + 4) = (f32x4){o[4], o[5], o[6], o[7]}; }
;                     else *(u32x4*)(XBout + off + bj * 128) = pack8(o); }
.LBB0_2002:
	global_load_dwordx4 v[74:77], v[82:83], off offset:256
	s_nop 0
	s_nop 1
	v_mov_b32_e32 v78, v242
	v_mov_b32_e32 v79, v243
	v_mov_b32_e32 v80, v244
	v_mov_b32_e32 v81, v245
	v_mov_b32_e32 v90, v246
	v_mov_b32_e32 v91, v247
	v_mov_b32_e32 v92, v248
	v_mov_b32_e32 v93, v249
	v_mov_b32_e32 v94, v250
	v_mov_b32_e32 v95, v251
	v_mov_b32_e32 v96, v252
	v_mov_b32_e32 v97, v253
	v_mov_b32_e32 v98, v186
	v_mov_b32_e32 v99, v187
	v_mov_b32_e32 v100, v196
	v_mov_b32_e32 v101, v197
	v_mov_b32_e32 v85, v84
	v_mov_b32_e32 v87, v86
	s_and_b64 vcc, exec, s[18:19]
	s_waitcnt vmcnt(0)
	v_lshlrev_b32_e32 v102, 16, v74
	v_and_b32_e32 v103, 0xffff0000, v74
	v_lshlrev_b32_e32 v74, 16, v75
	v_and_b32_e32 v75, 0xffff0000, v75
	v_pk_add_f32 v[74:75], v[74:75], v[84:85] neg_lo:[0,1] neg_hi:[0,1]
	v_pk_add_f32 v[102:103], v[102:103], v[84:85] neg_lo:[0,1] neg_hi:[0,1]
	v_pk_mul_f32 v[74:75], v[86:87], v[74:75]
	v_pk_mul_f32 v[102:103], v[86:87], v[102:103]
	s_waitcnt vmcnt(0)
	v_pk_fma_f32 v[74:75], v[92:93], v[74:75], v[100:101]
	v_pk_fma_f32 v[90:91], v[90:91], v[102:103], v[98:99]
	v_pk_fma_f32 v[72:73], v[74:75], s[86:87], v[72:73] op_sel_hi:[1,0,1]
	v_lshlrev_b32_e32 v74, 16, v76
	v_and_b32_e32 v75, 0xffff0000, v76
	v_pk_add_f32 v[74:75], v[74:75], v[84:85] neg_lo:[0,1] neg_hi:[0,1]
	v_pk_fma_f32 v[70:71], v[90:91], s[86:87], v[70:71] op_sel_hi:[1,0,1]
	v_pk_mul_f32 v[74:75], v[86:87], v[74:75]
	s_nop 0
	v_pk_fma_f32 v[74:75], v[78:79], v[74:75], v[94:95]
	s_nop 0
	v_pk_fma_f32 v[66:67], v[74:75], s[86:87], v[66:67] op_sel_hi:[1,0,1]
	v_lshlrev_b32_e32 v74, 16, v77
	v_and_b32_e32 v75, 0xffff0000, v77
	v_pk_add_f32 v[74:75], v[74:75], v[84:85] neg_lo:[0,1] neg_hi:[0,1]
	s_nop 0
	v_pk_mul_f32 v[74:75], v[86:87], v[74:75]
	s_nop 0
	v_pk_fma_f32 v[74:75], v[80:81], v[74:75], v[96:97]
	s_nop 0
	v_pk_fma_f32 v[68:69], v[74:75], s[86:87], v[68:69] op_sel_hi:[1,0,1]
	s_cbranch_vccnz .LBB0_2038
	global_store_dwordx4 v[88:89], v[70:73], off offset:512
	global_store_dwordx4 v[88:89], v[66:69], off offset:528
	s_cbranch_execnz .LBB0_2005

; DI float bperm(float v, int srclane) { return __int_as_float(__builtin_amdgcn_ds_bpermute(srclane << 2, __float_as_int(v))); }
; DI u32x4 pack8(const float (&v)[8]) { u32x4 w; w.x = pk2(v[0], v[1]); w.y = pk2(v[2], v[3]); w.z = pk2(v[4], v[5]); w.w = pk2(v[6], v[7]); return w; }
; DI void row_stats(const float* STAT, int row, int fq, int lane, float& mu, float& rstd) {
;     const f32x4 a = *(const f32x4*)(STAT + (size_t)row * 32 + fq * 8), b = *(const f32x4*)(STAT + (size_t)row * 32 + fq * 8 + 4);
;     float s = (a[0] + a[2]) + (b[0] + b[2]), q = (a[1] + a[3]) + (b[1] + b[3]);
;     s += bperm(s, lane ^ 16); q += bperm(q, lane ^ 16); s += bperm(s, lane ^ 32); q += bperm(q, lane ^ 32);
;     mu = s * (1.0f / 1024.0f); rstd = __builtin_amdgcn_rsqf(fmaxf(q * (1.0f / 1024.0f) - mu * mu, 0.f) + EPS);
;     DI void operator()(const f32x4 (&acc)[2][2][4][2], const pg8::Unit& u, int wr, int wc, int fr, int fq) const {
;     ...
;             for (int m = 0; m < 4; ++m) { const int row = row0 + ai * 128 + m * 16; const size_t off = (size_t)row * DMODEL + col0; float mu, rstd; row_stats(STAT, row, fq, lane, mu, rstd);
; #pragma unroll
;                 for (int bj = 0; bj < 2; ++bj) { float p[8]; unpack8(*(const u32x4*)(XBin + off + bj * 128), p);
;                     const f32x4 g0 = *(const f32x4*)(g + col0 + bj * 128), g1 = *(const f32x4*)(g + col0 + bj * 128 + 4), b0 = *(const f32x4*)(b + col0 + bj * 128), b1 = *(const f32x4*)(b + col0 + bj * 128 + 4);
;                     float o[8];
; #pragma unroll
;                     for (int k = 0; k < 8; ++k) { const float gg = k < 4 ? g0[k & 3] : g1[k & 3], bb = k < 4 ? b0[k & 3] : b1[k & 3]; const float x1 = (p[k] - mu) * rstd * gg + bb; o[k] = x1 * ALPHA + acc[ai][bj][m][k >> 2][k & 3]; }
;                     if (out32) { *(f32x4*)(out32 + off + bj * 128) = (f32x4){o[0], o[1], o[2], o[3]}; *(f32x4*)(out32 + off + bj * 128 + 4) = (f32x4){o[4], o[5], o[6], o[7]}; }
;                     else *(u32x4*)(XBout + off + bj * 128) = pack8(o); }
.LBB0_2005:
	s_nop 0
	v_add_u32_e32 v66, 0x80, v146
	v_ashrrev_i32_e32 v67, 31, v66
	v_lshlrev_b64 v[68:69], 10, v[66:67]
	v_lshlrev_b64 v[66:67], 7, v[66:67]
	v_lshl_add_u64 v[66:67], s[36:37], 0, v[66:67]
	v_lshl_add_u64 v[70:71], v[144:145], 2, v[66:67]
	v_lshl_add_u64 v[72:73], v[68:69], 0, v[148:149]
	global_load_dwordx4 v[66:69], v[70:71], off offset:16
	global_load_dwordx4 v[74:77], v[70:71], off
	s_mov_b32 s2, 0x3a800000
	s_and_b64 vcc, exec, s[18:19]
	s_waitcnt vmcnt(1)
	v_pk_add_f32 v[66:67], v[66:67], v[68:69]
	s_waitcnt vmcnt(0)
	v_pk_add_f32 v[70:71], v[74:75], v[76:77]
	s_nop 0
	v_pk_add_f32 v[66:67], v[70:71], v[66:67]
	ds_bpermute_b32 v68, v163, v66
	ds_bpermute_b32 v69, v163, v67
	s_waitcnt lgkmcnt(0)
	v_pk_add_f32 v[66:67], v[66:67], v[68:69]
	ds_bpermute_b32 v68, v162, v66
	ds_bpermute_b32 v69, v162, v67
	s_waitcnt lgkmcnt(0)
	v_pk_add_f32 v[66:67], v[66:67], v[68:69]
	s_nop 0
	v_pk_mul_f32 v[68:69], v[66:67], s[2:3] op_sel_hi:[1,0]
	s_nop 0
	v_fma_f32 v66, -v68, v68, v69
	v_max_f32_e32 v66, 0, v66
	v_add_f32_e32 v66, 0x3727c5ac, v66
	v_rsq_f32_e32 v70, v66
	v_lshl_add_u64 v[66:67], v[72:73], 1, s[26:27]
	global_load_dwordx4 v[74:77], v[66:67], off
	s_nop 1
	v_mov_b32_e32 v78, v220
	v_mov_b32_e32 v79, v221
	v_mov_b32_e32 v80, v222
	v_mov_b32_e32 v81, v223
	v_mov_b32_e32 v82, v224
	v_mov_b32_e32 v83, v225
	v_mov_b32_e32 v84, v226
	v_mov_b32_e32 v85, v227
	v_mov_b32_e32 v86, v228
	v_mov_b32_e32 v87, v229
	v_mov_b32_e32 v88, v230
	v_mov_b32_e32 v89, v231
	v_mov_b32_e32 v90, v232
	v_mov_b32_e32 v91, v233
	v_mov_b32_e32 v92, v234
	v_mov_b32_e32 v93, v235
	v_lshl_add_u64 v[72:73], v[72:73], 2, s[28:29]
	s_waitcnt vmcnt(0)
	v_lshlrev_b32_e32 v94, 16, v74
	v_and_b32_e32 v95, 0xffff0000, v74
	v_lshlrev_b32_e32 v74, 16, v75
	v_and_b32_e32 v75, 0xffff0000, v75
	v_pk_add_f32 v[74:75], v[74:75], v[68:69] op_sel_hi:[1,0] neg_lo:[0,1] neg_hi:[0,1]
	v_pk_add_f32 v[94:95], v[94:95], v[68:69] op_sel_hi:[1,0] neg_lo:[0,1] neg_hi:[0,1]
	v_pk_mul_f32 v[74:75], v[74:75], v[70:71] op_sel_hi:[1,0]
	v_pk_mul_f32 v[94:95], v[94:95], v[70:71] op_sel_hi:[1,0]
	s_waitcnt vmcnt(0)
	v_pk_fma_f32 v[74:75], v[84:85], v[74:75], v[92:93]
	v_pk_fma_f32 v[82:83], v[82:83], v[94:95], v[90:91]
	v_pk_fma_f32 v[64:65], v[74:75], s[86:87], v[64:65] op_sel_hi:[1,0,1]
	v_lshlrev_b32_e32 v74, 16, v76
	v_and_b32_e32 v75, 0xffff0000, v76
	v_pk_add_f32 v[74:75], v[74:75], v[68:69] op_sel_hi:[1,0] neg_lo:[0,1] neg_hi:[0,1]
	v_pk_fma_f32 v[62:63], v[82:83], s[86:87], v[62:63] op_sel_hi:[1,0,1]
	v_pk_mul_f32 v[74:75], v[74:75], v[70:71] op_sel_hi:[1,0]
	s_nop 0
	v_pk_fma_f32 v[74:75], v[78:79], v[74:75], v[86:87]
	s_nop 0
	v_pk_fma_f32 v[58:59], v[74:75], s[86:87], v[58:59] op_sel_hi:[1,0,1]
	v_lshlrev_b32_e32 v74, 16, v77
	v_and_b32_e32 v75, 0xffff0000, v77
	v_pk_add_f32 v[74:75], v[74:75], v[68:69] op_sel_hi:[1,0] neg_lo:[0,1] neg_hi:[0,1]
	s_nop 0
	v_pk_mul_f32 v[74:75], v[74:75], v[70:71] op_sel_hi:[1,0]
	s_nop 0
	v_pk_fma_f32 v[74:75], v[80:81], v[74:75], v[88:89]
	s_nop 0
	v_pk_fma_f32 v[60:61], v[74:75], s[86:87], v[60:61] op_sel_hi:[1,0,1]
	s_cbranch_vccnz .LBB0_2039
	global_store_dwordx4 v[72:73], v[62:65], off
	global_store_dwordx4 v[72:73], v[58:61], off offset:16
	s_cbranch_execnz .LBB0_2008

; DI u32x4 pack8(const float (&v)[8]) { u32x4 w; w.x = pk2(v[0], v[1]); w.y = pk2(v[2], v[3]); w.z = pk2(v[4], v[5]); w.w = pk2(v[6], v[7]); return w; }
;     DI void operator()(const f32x4 (&acc)[2][2][4][2], const pg8::Unit& u, int wr, int wc, int fr, int fq) const {
;     ...
;                 for (int bj = 0; bj < 2; ++bj) { float p[8]; unpack8(*(const u32x4*)(XBin + off + bj * 128), p);
;                     const f32x4 g0 = *(const f32x4*)(g + col0 + bj * 128), g1 = *(const f32x4*)(g + col0 + bj * 128 + 4), b0 = *(const f32x4*)(b + col0 + bj * 128), b1 = *(const f32x4*)(b + col0 + bj * 128 + 4);
;                     float o[8];
; #pragma unroll
;                     for (int k = 0; k < 8; ++k) { const float gg = k < 4 ? g0[k & 3] : g1[k & 3], bb = k < 4 ? b0[k & 3] : b1[k & 3]; const float x1 = (p[k] - mu) * rstd * gg + bb; o[k] = x1 * ALPHA + acc[ai][bj][m][k >> 2][k & 3]; }
;                     if (out32) { *(f32x4*)(out32 + off + bj * 128) = (f32x4){o[0], o[1], o[2], o[3]}; *(f32x4*)(out32 + off + bj * 128 + 4) = (f32x4){o[4], o[5], o[6], o[7]}; }
;                     else *(u32x4*)(XBout + off + bj * 128) = pack8(o); }
.LBB0_2008:
	global_load_dwordx4 v[58:61], v[66:67], off offset:256
	s_nop 0
	s_nop 1
	v_mov_b32_e32 v62, v242
	v_mov_b32_e32 v63, v243
	v_mov_b32_e32 v64, v244
	v_mov_b32_e32 v65, v245
	v_mov_b32_e32 v74, v246
	v_mov_b32_e32 v75, v247
	v_mov_b32_e32 v76, v248
	v_mov_b32_e32 v77, v249
	v_mov_b32_e32 v78, v250
	v_mov_b32_e32 v79, v251
	v_mov_b32_e32 v80, v252
	v_mov_b32_e32 v81, v253
	v_mov_b32_e32 v82, v186
	v_mov_b32_e32 v83, v187
	v_mov_b32_e32 v84, v196
	v_mov_b32_e32 v85, v197
	v_mov_b32_e32 v69, v68
	v_mov_b32_e32 v71, v70
	s_and_b64 vcc, exec, s[18:19]
	s_waitcnt vmcnt(0)
	v_lshlrev_b32_e32 v86, 16, v58
	v_and_b32_e32 v87, 0xffff0000, v58
	v_lshlrev_b32_e32 v58, 16, v59
	v_and_b32_e32 v59, 0xffff0000, v59
	v_pk_add_f32 v[58:59], v[58:59], v[68:69] neg_lo:[0,1] neg_hi:[0,1]
	v_pk_add_f32 v[86:87], v[86:87], v[68:69] neg_lo:[0,1] neg_hi:[0,1]
	v_pk_mul_f32 v[58:59], v[70:71], v[58:59]
	v_pk_mul_f32 v[86:87], v[70:71], v[86:87]
	s_waitcnt vmcnt(0)
	v_pk_fma_f32 v[58:59], v[76:77], v[58:59], v[84:85]
	v_pk_fma_f32 v[74:75], v[74:75], v[86:87], v[82:83]
	v_pk_fma_f32 v[56:57], v[58:59], s[86:87], v[56:57] op_sel_hi:[1,0,1]
	v_lshlrev_b32_e32 v58, 16, v60
	v_and_b32_e32 v59, 0xffff0000, v60
	v_pk_add_f32 v[58:59], v[58:59], v[68:69] neg_lo:[0,1] neg_hi:[0,1]
	v_pk_fma_f32 v[54:55], v[74:75], s[86:87], v[54:55] op_sel_hi:[1,0,1]
	v_pk_mul_f32 v[58:59], v[70:71], v[58:59]
	s_nop 0
	v_pk_fma_f32 v[58:59], v[62:63], v[58:59], v[78:79]
	s_nop 0
	v_pk_fma_f32 v[50:51], v[58:59], s[86:87], v[50:51] op_sel_hi:[1,0,1]
	v_lshlrev_b32_e32 v58, 16, v61
	v_and_b32_e32 v59, 0xffff0000, v61
	v_pk_add_f32 v[58:59], v[58:59], v[68:69] neg_lo:[0,1] neg_hi:[0,1]
	s_nop 0
	v_pk_mul_f32 v[58:59], v[70:71], v[58:59]
	s_nop 0
	v_pk_fma_f32 v[58:59], v[64:65], v[58:59], v[80:81]
	s_nop 0
	v_pk_fma_f32 v[52:53], v[58:59], s[86:87], v[52:53] op_sel_hi:[1,0,1]
	s_cbranch_vccnz .LBB0_2040
	global_store_dwordx4 v[72:73], v[54:57], off offset:512
	global_store_dwordx4 v[72:73], v[50:53], off offset:528
	s_cbranch_execnz .LBB0_2011

; DI float bperm(float v, int srclane) { return __int_as_float(__builtin_amdgcn_ds_bpermute(srclane << 2, __float_as_int(v))); }
; DI u32x4 pack8(const float (&v)[8]) { u32x4 w; w.x = pk2(v[0], v[1]); w.y = pk2(v[2], v[3]); w.z = pk2(v[4], v[5]); w.w = pk2(v[6], v[7]); return w; }
; DI void row_stats(const float* STAT, int row, int fq, int lane, float& mu, float& rstd) {
;     const f32x4 a = *(const f32x4*)(STAT + (size_t)row * 32 + fq * 8), b = *(const f32x4*)(STAT + (size_t)row * 32 + fq * 8 + 4);
;     float s = (a[0] + a[2]) + (b[0] + b[2]), q = (a[1] + a[3]) + (b[1] + b[3]);
;     s += bperm(s, lane ^ 16); q += bperm(q, lane ^ 16); s += bperm(s, lane ^ 32); q += bperm(q, lane ^ 32);
;     mu = s * (1.0f / 1024.0f); rstd = __builtin_amdgcn_rsqf(fmaxf(q * (1.0f / 1024.0f) - mu * mu, 0.f) + EPS);
;     DI void operator()(const f32x4 (&acc)[2][2][4][2], const pg8::Unit& u, int wr, int wc, int fr, int fq) const {
;     ...
;             for (int m = 0; m < 4; ++m) { const int row = row0 + ai * 128 + m * 16; const size_t off = (size_t)row * DMODEL + col0; float mu, rstd; row_stats(STAT, row, fq, lane, mu, rstd);
; #pragma unroll
;                 for (int bj = 0; bj < 2; ++bj) { float p[8]; unpack8(*(const u32x4*)(XBin + off + bj * 128), p);
;                     const f32x4 g0 = *(const f32x4*)(g + col0 + bj * 128), g1 = *(const f32x4*)(g + col0 + bj * 128 + 4), b0 = *(const f32x4*)(b + col0 + bj * 128), b1 = *(const f32x4*)(b + col0 + bj * 128 + 4);
;                     float o[8];
; #pragma unroll
;                     for (int k = 0; k < 8; ++k) { const float gg = k < 4 ? g0[k & 3] : g1[k & 3], bb = k < 4 ? b0[k & 3] : b1[k & 3]; const float x1 = (p[k] - mu) * rstd * gg + bb; o[k] = x1 * ALPHA + acc[ai][bj][m][k >> 2][k & 3]; }
;                     if (out32) { *(f32x4*)(out32 + off + bj * 128) = (f32x4){o[0], o[1], o[2], o[3]}; *(f32x4*)(out32 + off + bj * 128 + 4) = (f32x4){o[4], o[5], o[6], o[7]}; }
;                     else *(u32x4*)(XBout + off + bj * 128) = pack8(o); }
.LBB0_2011:
	s_nop 0
	v_add_u32_e32 v50, 0x90, v146
	v_ashrrev_i32_e32 v51, 31, v50
	v_lshlrev_b64 v[52:53], 10, v[50:51]
	v_lshlrev_b64 v[50:51], 7, v[50:51]
	v_lshl_add_u64 v[50:51], s[36:37], 0, v[50:51]
	v_lshl_add_u64 v[54:55], v[144:145], 2, v[50:51]
	s_nop 1
	v_mov_b32_e32 v58, v220
	v_mov_b32_e32 v59, v221
	v_mov_b32_e32 v60, v222
	v_mov_b32_e32 v61, v223
	v_mov_b32_e32 v62, v224
	v_mov_b32_e32 v63, v225
	v_mov_b32_e32 v64, v226
	v_mov_b32_e32 v65, v227
	v_mov_b32_e32 v66, v228
	v_mov_b32_e32 v67, v229
	v_mov_b32_e32 v68, v230
	v_mov_b32_e32 v69, v231
	v_mov_b32_e32 v70, v232
	v_mov_b32_e32 v71, v233
	v_mov_b32_e32 v72, v234
	v_mov_b32_e32 v73, v235
	v_lshl_add_u64 v[56:57], v[52:53], 0, v[148:149]
	global_load_dwordx4 v[50:53], v[54:55], off offset:16
	global_load_dwordx4 v[74:77], v[54:55], off
	s_mov_b32 s2, 0x3a800000
	s_and_b64 vcc, exec, s[18:19]
	s_waitcnt vmcnt(1)
	v_pk_add_f32 v[50:51], v[50:51], v[52:53]
	s_waitcnt vmcnt(0)
	v_pk_add_f32 v[54:55], v[74:75], v[76:77]
	s_nop 0
	v_pk_add_f32 v[50:51], v[54:55], v[50:51]
	ds_bpermute_b32 v52, v163, v50
	ds_bpermute_b32 v53, v163, v51
	s_waitcnt lgkmcnt(0)
	v_pk_add_f32 v[50:51], v[50:51], v[52:53]
	ds_bpermute_b32 v52, v162, v50
	ds_bpermute_b32 v53, v162, v51
	s_waitcnt lgkmcnt(0)
	v_pk_add_f32 v[50:51], v[50:51], v[52:53]
	s_nop 0
	v_pk_mul_f32 v[52:53], v[50:51], s[2:3] op_sel_hi:[1,0]
	s_nop 0
	v_fma_f32 v50, -v52, v52, v53
	v_max_f32_e32 v50, 0, v50
	v_add_f32_e32 v50, 0x3727c5ac, v50
	v_rsq_f32_e32 v54, v50
	v_lshl_add_u64 v[50:51], v[56:57], 1, s[26:27]
	global_load_dwordx4 v[74:77], v[50:51], off
	v_lshl_add_u64 v[56:57], v[56:57], 2, s[28:29]
	s_waitcnt vmcnt(0)
	v_lshlrev_b32_e32 v78, 16, v74
	v_and_b32_e32 v79, 0xffff0000, v74
	v_pk_add_f32 v[78:79], v[78:79], v[52:53] op_sel_hi:[1,0] neg_lo:[0,1] neg_hi:[0,1]
	s_nop 0
	v_pk_mul_f32 v[78:79], v[78:79], v[54:55] op_sel_hi:[1,0]
	s_nop 0
	v_pk_fma_f32 v[62:63], v[62:63], v[78:79], v[70:71]
	s_nop 0
	v_pk_fma_f32 v[46:47], v[62:63], s[86:87], v[46:47] op_sel_hi:[1,0,1]
	v_lshlrev_b32_e32 v62, 16, v75
	v_and_b32_e32 v63, 0xffff0000, v75
	v_pk_add_f32 v[62:63], v[62:63], v[52:53] op_sel_hi:[1,0] neg_lo:[0,1] neg_hi:[0,1]
	s_nop 0
	v_pk_mul_f32 v[62:63], v[62:63], v[54:55] op_sel_hi:[1,0]
	s_nop 0
	v_pk_fma_f32 v[62:63], v[64:65], v[62:63], v[72:73]
	s_nop 0
	v_pk_fma_f32 v[48:49], v[62:63], s[86:87], v[48:49] op_sel_hi:[1,0,1]
	v_lshlrev_b32_e32 v62, 16, v76
	v_and_b32_e32 v63, 0xffff0000, v76
	v_pk_add_f32 v[62:63], v[62:63], v[52:53] op_sel_hi:[1,0] neg_lo:[0,1] neg_hi:[0,1]
	s_nop 0
	v_pk_mul_f32 v[62:63], v[62:63], v[54:55] op_sel_hi:[1,0]
	s_nop 0
	v_pk_fma_f32 v[58:59], v[58:59], v[62:63], v[66:67]
	s_nop 0
	v_pk_fma_f32 v[42:43], v[58:59], s[86:87], v[42:43] op_sel_hi:[1,0,1]
	v_lshlrev_b32_e32 v58, 16, v77
	v_and_b32_e32 v59, 0xffff0000, v77
	v_pk_add_f32 v[58:59], v[58:59], v[52:53] op_sel_hi:[1,0] neg_lo:[0,1] neg_hi:[0,1]
	s_nop 0
	v_pk_mul_f32 v[58:59], v[58:59], v[54:55] op_sel_hi:[1,0]
	s_nop 0
	v_pk_fma_f32 v[58:59], v[60:61], v[58:59], v[68:69]
	s_nop 0
	v_pk_fma_f32 v[44:45], v[58:59], s[86:87], v[44:45] op_sel_hi:[1,0,1]
	s_cbranch_vccnz .LBB0_2041
	global_store_dwordx4 v[56:57], v[46:49], off
	global_store_dwordx4 v[56:57], v[42:45], off offset:16
	s_cbranch_execnz .LBB0_2014

; DI u32x4 pack8(const float (&v)[8]) { u32x4 w; w.x = pk2(v[0], v[1]); w.y = pk2(v[2], v[3]); w.z = pk2(v[4], v[5]); w.w = pk2(v[6], v[7]); return w; }
;     DI void operator()(const f32x4 (&acc)[2][2][4][2], const pg8::Unit& u, int wr, int wc, int fr, int fq) const {
;     ...
;                 for (int bj = 0; bj < 2; ++bj) { float p[8]; unpack8(*(const u32x4*)(XBin + off + bj * 128), p);
;                     const f32x4 g0 = *(const f32x4*)(g + col0 + bj * 128), g1 = *(const f32x4*)(g + col0 + bj * 128 + 4), b0 = *(const f32x4*)(b + col0 + bj * 128), b1 = *(const f32x4*)(b + col0 + bj * 128 + 4);
;                     float o[8];
; #pragma unroll
;                     for (int k = 0; k < 8; ++k) { const float gg = k < 4 ? g0[k & 3] : g1[k & 3], bb = k < 4 ? b0[k & 3] : b1[k & 3]; const float x1 = (p[k] - mu) * rstd * gg + bb; o[k] = x1 * ALPHA + acc[ai][bj][m][k >> 2][k & 3]; }
;                     if (out32) { *(f32x4*)(out32 + off + bj * 128) = (f32x4){o[0], o[1], o[2], o[3]}; *(f32x4*)(out32 + off + bj * 128 + 4) = (f32x4){o[4], o[5], o[6], o[7]}; }
;                     else *(u32x4*)(XBout + off + bj * 128) = pack8(o); }
.LBB0_2014:
	global_load_dwordx4 v[42:45], v[50:51], off offset:256
	s_nop 0
	s_nop 1
	v_mov_b32_e32 v46, v242
	v_mov_b32_e32 v47, v243
	v_mov_b32_e32 v48, v244
	v_mov_b32_e32 v49, v245
	v_mov_b32_e32 v58, v246
	v_mov_b32_e32 v59, v247
	v_mov_b32_e32 v60, v248
	v_mov_b32_e32 v61, v249
	v_mov_b32_e32 v62, v250
	v_mov_b32_e32 v63, v251
	v_mov_b32_e32 v64, v252
	v_mov_b32_e32 v65, v253
	v_mov_b32_e32 v66, v186
	v_mov_b32_e32 v67, v187
	v_mov_b32_e32 v68, v196
	v_mov_b32_e32 v69, v197
	v_mov_b32_e32 v53, v52
	v_mov_b32_e32 v55, v54
	s_and_b64 vcc, exec, s[18:19]
	s_waitcnt vmcnt(0)
	v_lshlrev_b32_e32 v70, 16, v42
	v_and_b32_e32 v71, 0xffff0000, v42
	v_lshlrev_b32_e32 v42, 16, v43
	v_and_b32_e32 v43, 0xffff0000, v43
	v_pk_add_f32 v[42:43], v[42:43], v[52:53] neg_lo:[0,1] neg_hi:[0,1]
	v_pk_add_f32 v[70:71], v[70:71], v[52:53] neg_lo:[0,1] neg_hi:[0,1]
	v_pk_mul_f32 v[42:43], v[54:55], v[42:43]
	v_pk_mul_f32 v[70:71], v[54:55], v[70:71]
	s_waitcnt vmcnt(0)
	v_pk_fma_f32 v[42:43], v[60:61], v[42:43], v[68:69]
	v_pk_fma_f32 v[58:59], v[58:59], v[70:71], v[66:67]
	v_pk_fma_f32 v[40:41], v[42:43], s[86:87], v[40:41] op_sel_hi:[1,0,1]
	v_lshlrev_b32_e32 v42, 16, v44
	v_and_b32_e32 v43, 0xffff0000, v44
	v_pk_add_f32 v[42:43], v[42:43], v[52:53] neg_lo:[0,1] neg_hi:[0,1]
	v_pk_fma_f32 v[38:39], v[58:59], s[86:87], v[38:39] op_sel_hi:[1,0,1]
	v_pk_mul_f32 v[42:43], v[54:55], v[42:43]
	s_nop 0
	v_pk_fma_f32 v[42:43], v[46:47], v[42:43], v[62:63]
	s_nop 0
	v_pk_fma_f32 v[34:35], v[42:43], s[86:87], v[34:35] op_sel_hi:[1,0,1]
	v_lshlrev_b32_e32 v42, 16, v45
	v_and_b32_e32 v43, 0xffff0000, v45
	v_pk_add_f32 v[42:43], v[42:43], v[52:53] neg_lo:[0,1] neg_hi:[0,1]
	s_nop 0
	v_pk_mul_f32 v[42:43], v[54:55], v[42:43]
	s_nop 0
	v_pk_fma_f32 v[42:43], v[48:49], v[42:43], v[64:65]
	s_nop 0
	v_pk_fma_f32 v[36:37], v[42:43], s[86:87], v[36:37] op_sel_hi:[1,0,1]
	s_cbranch_vccnz .LBB0_2042
	global_store_dwordx4 v[56:57], v[38:41], off offset:512
	global_store_dwordx4 v[56:57], v[34:37], off offset:528
	s_cbranch_execnz .LBB0_2017

; DI float bperm(float v, int srclane) { return __int_as_float(__builtin_amdgcn_ds_bpermute(srclane << 2, __float_as_int(v))); }
; DI u32x4 pack8(const float (&v)[8]) { u32x4 w; w.x = pk2(v[0], v[1]); w.y = pk2(v[2], v[3]); w.z = pk2(v[4], v[5]); w.w = pk2(v[6], v[7]); return w; }
; DI void row_stats(const float* STAT, int row, int fq, int lane, float& mu, float& rstd) {
;     const f32x4 a = *(const f32x4*)(STAT + (size_t)row * 32 + fq * 8), b = *(const f32x4*)(STAT + (size_t)row * 32 + fq * 8 + 4);
;     float s = (a[0] + a[2]) + (b[0] + b[2]), q = (a[1] + a[3]) + (b[1] + b[3]);
;     s += bperm(s, lane ^ 16); q += bperm(q, lane ^ 16); s += bperm(s, lane ^ 32); q += bperm(q, lane ^ 32);
;     mu = s * (1.0f / 1024.0f); rstd = __builtin_amdgcn_rsqf(fmaxf(q * (1.0f / 1024.0f) - mu * mu, 0.f) + EPS);
;     DI void operator()(const f32x4 (&acc)[2][2][4][2], const pg8::Unit& u, int wr, int wc, int fr, int fq) const {
;     ...
;             for (int m = 0; m < 4; ++m) { const int row = row0 + ai * 128 + m * 16; const size_t off = (size_t)row * DMODEL + col0; float mu, rstd; row_stats(STAT, row, fq, lane, mu, rstd);
; #pragma unroll
;                 for (int bj = 0; bj < 2; ++bj) { float p[8]; unpack8(*(const u32x4*)(XBin + off + bj * 128), p);
;                     const f32x4 g0 = *(const f32x4*)(g + col0 + bj * 128), g1 = *(const f32x4*)(g + col0 + bj * 128 + 4), b0 = *(const f32x4*)(b + col0 + bj * 128), b1 = *(const f32x4*)(b + col0 + bj * 128 + 4);
;                     float o[8];
; #pragma unroll
;                     for (int k = 0; k < 8; ++k) { const float gg = k < 4 ? g0[k & 3] : g1[k & 3], bb = k < 4 ? b0[k & 3] : b1[k & 3]; const float x1 = (p[k] - mu) * rstd * gg + bb; o[k] = x1 * ALPHA + acc[ai][bj][m][k >> 2][k & 3]; }
;                     if (out32) { *(f32x4*)(out32 + off + bj * 128) = (f32x4){o[0], o[1], o[2], o[3]}; *(f32x4*)(out32 + off + bj * 128 + 4) = (f32x4){o[4], o[5], o[6], o[7]}; }
;                     else *(u32x4*)(XBout + off + bj * 128) = pack8(o); }
.LBB0_2017:
	s_nop 0
	v_add_u32_e32 v34, 0xa0, v146
	v_ashrrev_i32_e32 v35, 31, v34
	v_lshlrev_b64 v[36:37], 10, v[34:35]
	v_lshlrev_b64 v[34:35], 7, v[34:35]
	v_lshl_add_u64 v[34:35], s[36:37], 0, v[34:35]
	v_lshl_add_u64 v[38:39], v[144:145], 2, v[34:35]
	s_nop 1
	v_mov_b32_e32 v42, v220
	v_mov_b32_e32 v43, v221
	v_mov_b32_e32 v44, v222
	v_mov_b32_e32 v45, v223
	v_mov_b32_e32 v46, v224
	v_mov_b32_e32 v47, v225
	v_mov_b32_e32 v48, v226
	v_mov_b32_e32 v49, v227
	v_mov_b32_e32 v50, v228
	v_mov_b32_e32 v51, v229
	v_mov_b32_e32 v52, v230
	v_mov_b32_e32 v53, v231
	v_mov_b32_e32 v54, v232
	v_mov_b32_e32 v55, v233
	v_mov_b32_e32 v56, v234
	v_mov_b32_e32 v57, v235
	v_lshl_add_u64 v[40:41], v[36:37], 0, v[148:149]
	global_load_dwordx4 v[34:37], v[38:39], off offset:16
	global_load_dwordx4 v[58:61], v[38:39], off
	s_mov_b32 s2, 0x3a800000
	s_and_b64 vcc, exec, s[18:19]
	s_waitcnt vmcnt(1)
	v_pk_add_f32 v[34:35], v[34:35], v[36:37]
	s_waitcnt vmcnt(0)
	v_pk_add_f32 v[38:39], v[58:59], v[60:61]
	s_nop 0
	v_pk_add_f32 v[34:35], v[38:39], v[34:35]
	ds_bpermute_b32 v36, v163, v34
	ds_bpermute_b32 v37, v163, v35
	s_waitcnt lgkmcnt(0)
	v_pk_add_f32 v[34:35], v[34:35], v[36:37]
	ds_bpermute_b32 v36, v162, v34
	ds_bpermute_b32 v37, v162, v35
	s_waitcnt lgkmcnt(0)
	v_pk_add_f32 v[34:35], v[34:35], v[36:37]
	s_nop 0
	v_pk_mul_f32 v[36:37], v[34:35], s[2:3] op_sel_hi:[1,0]
	s_nop 0
	v_fma_f32 v34, -v36, v36, v37
	v_max_f32_e32 v34, 0, v34
	v_add_f32_e32 v34, 0x3727c5ac, v34
	v_rsq_f32_e32 v38, v34
	v_lshl_add_u64 v[34:35], v[40:41], 1, s[26:27]
	global_load_dwordx4 v[58:61], v[34:35], off
	v_lshl_add_u64 v[40:41], v[40:41], 2, s[28:29]
	s_waitcnt vmcnt(0)
	v_lshlrev_b32_e32 v62, 16, v58
	v_and_b32_e32 v63, 0xffff0000, v58
	v_pk_add_f32 v[62:63], v[62:63], v[36:37] op_sel_hi:[1,0] neg_lo:[0,1] neg_hi:[0,1]
	s_nop 0
	v_pk_mul_f32 v[62:63], v[62:63], v[38:39] op_sel_hi:[1,0]
	s_nop 0
	v_pk_fma_f32 v[46:47], v[46:47], v[62:63], v[54:55]
	s_nop 0
	v_pk_fma_f32 v[30:31], v[46:47], s[86:87], v[30:31] op_sel_hi:[1,0,1]
	v_lshlrev_b32_e32 v46, 16, v59
	v_and_b32_e32 v47, 0xffff0000, v59
	v_pk_add_f32 v[46:47], v[46:47], v[36:37] op_sel_hi:[1,0] neg_lo:[0,1] neg_hi:[0,1]
	s_nop 0
	v_pk_mul_f32 v[46:47], v[46:47], v[38:39] op_sel_hi:[1,0]
	s_nop 0
	v_pk_fma_f32 v[46:47], v[48:49], v[46:47], v[56:57]
	s_nop 0
	v_pk_fma_f32 v[32:33], v[46:47], s[86:87], v[32:33] op_sel_hi:[1,0,1]
	v_lshlrev_b32_e32 v46, 16, v60
	v_and_b32_e32 v47, 0xffff0000, v60
	v_pk_add_f32 v[46:47], v[46:47], v[36:37] op_sel_hi:[1,0] neg_lo:[0,1] neg_hi:[0,1]
	s_nop 0
	v_pk_mul_f32 v[46:47], v[46:47], v[38:39] op_sel_hi:[1,0]
	s_nop 0
	v_pk_fma_f32 v[42:43], v[42:43], v[46:47], v[50:51]
	s_nop 0
	v_pk_fma_f32 v[26:27], v[42:43], s[86:87], v[26:27] op_sel_hi:[1,0,1]
	v_lshlrev_b32_e32 v42, 16, v61
	v_and_b32_e32 v43, 0xffff0000, v61
	v_pk_add_f32 v[42:43], v[42:43], v[36:37] op_sel_hi:[1,0] neg_lo:[0,1] neg_hi:[0,1]
	s_nop 0
	v_pk_mul_f32 v[42:43], v[42:43], v[38:39] op_sel_hi:[1,0]
	s_nop 0
	v_pk_fma_f32 v[42:43], v[44:45], v[42:43], v[52:53]
	s_nop 0
	v_pk_fma_f32 v[28:29], v[42:43], s[86:87], v[28:29] op_sel_hi:[1,0,1]
	s_cbranch_vccnz .LBB0_2043
	global_store_dwordx4 v[40:41], v[30:33], off
	global_store_dwordx4 v[40:41], v[26:29], off offset:16
	s_cbranch_execnz .LBB0_2020

; DI u32x4 pack8(const float (&v)[8]) { u32x4 w; w.x = pk2(v[0], v[1]); w.y = pk2(v[2], v[3]); w.z = pk2(v[4], v[5]); w.w = pk2(v[6], v[7]); return w; }
;     DI void operator()(const f32x4 (&acc)[2][2][4][2], const pg8::Unit& u, int wr, int wc, int fr, int fq) const {
;     ...
;                 for (int bj = 0; bj < 2; ++bj) { float p[8]; unpack8(*(const u32x4*)(XBin + off + bj * 128), p);
;                     const f32x4 g0 = *(const f32x4*)(g + col0 + bj * 128), g1 = *(const f32x4*)(g + col0 + bj * 128 + 4), b0 = *(const f32x4*)(b + col0 + bj * 128), b1 = *(const f32x4*)(b + col0 + bj * 128 + 4);
;                     float o[8];
; #pragma unroll
;                     for (int k = 0; k < 8; ++k) { const float gg = k < 4 ? g0[k & 3] : g1[k & 3], bb = k < 4 ? b0[k & 3] : b1[k & 3]; const float x1 = (p[k] - mu) * rstd * gg + bb; o[k] = x1 * ALPHA + acc[ai][bj][m][k >> 2][k & 3]; }
;                     if (out32) { *(f32x4*)(out32 + off + bj * 128) = (f32x4){o[0], o[1], o[2], o[3]}; *(f32x4*)(out32 + off + bj * 128 + 4) = (f32x4){o[4], o[5], o[6], o[7]}; }
;                     else *(u32x4*)(XBout + off + bj * 128) = pack8(o); }
.LBB0_2020:
	global_load_dwordx4 v[26:29], v[34:35], off offset:256
	s_nop 0
	s_nop 1
	v_mov_b32_e32 v30, v242
	v_mov_b32_e32 v31, v243
	v_mov_b32_e32 v32, v244
	v_mov_b32_e32 v33, v245
	v_mov_b32_e32 v42, v246
	v_mov_b32_e32 v43, v247
	v_mov_b32_e32 v44, v248
	v_mov_b32_e32 v45, v249
	v_mov_b32_e32 v46, v250
	v_mov_b32_e32 v47, v251
	v_mov_b32_e32 v48, v252
	v_mov_b32_e32 v49, v253
	v_mov_b32_e32 v50, v186
	v_mov_b32_e32 v51, v187
	v_mov_b32_e32 v52, v196
	v_mov_b32_e32 v53, v197
	v_mov_b32_e32 v37, v36
	v_mov_b32_e32 v39, v38
	s_and_b64 vcc, exec, s[18:19]
	s_waitcnt vmcnt(0)
	v_lshlrev_b32_e32 v54, 16, v26
	v_and_b32_e32 v55, 0xffff0000, v26
	v_lshlrev_b32_e32 v26, 16, v27
	v_and_b32_e32 v27, 0xffff0000, v27
	v_pk_add_f32 v[26:27], v[26:27], v[36:37] neg_lo:[0,1] neg_hi:[0,1]
	v_pk_add_f32 v[54:55], v[54:55], v[36:37] neg_lo:[0,1] neg_hi:[0,1]
	v_pk_mul_f32 v[26:27], v[38:39], v[26:27]
	v_pk_mul_f32 v[54:55], v[38:39], v[54:55]
	s_waitcnt vmcnt(0)
	v_pk_fma_f32 v[26:27], v[44:45], v[26:27], v[52:53]
	v_pk_fma_f32 v[42:43], v[42:43], v[54:55], v[50:51]
	v_pk_fma_f32 v[24:25], v[26:27], s[86:87], v[24:25] op_sel_hi:[1,0,1]
	v_lshlrev_b32_e32 v26, 16, v28
	v_and_b32_e32 v27, 0xffff0000, v28
	v_pk_add_f32 v[26:27], v[26:27], v[36:37] neg_lo:[0,1] neg_hi:[0,1]
	v_pk_fma_f32 v[22:23], v[42:43], s[86:87], v[22:23] op_sel_hi:[1,0,1]
	v_pk_mul_f32 v[26:27], v[38:39], v[26:27]
	s_nop 0
	v_pk_fma_f32 v[26:27], v[30:31], v[26:27], v[46:47]
	s_nop 0
	v_pk_fma_f32 v[18:19], v[26:27], s[86:87], v[18:19] op_sel_hi:[1,0,1]
	v_lshlrev_b32_e32 v26, 16, v29
	v_and_b32_e32 v27, 0xffff0000, v29
	v_pk_add_f32 v[26:27], v[26:27], v[36:37] neg_lo:[0,1] neg_hi:[0,1]
	s_nop 0
	v_pk_mul_f32 v[26:27], v[38:39], v[26:27]
	s_nop 0
	v_pk_fma_f32 v[26:27], v[32:33], v[26:27], v[48:49]
	s_nop 0
	v_pk_fma_f32 v[20:21], v[26:27], s[86:87], v[20:21] op_sel_hi:[1,0,1]
	s_cbranch_vccnz .LBB0_2044
	global_store_dwordx4 v[40:41], v[22:25], off offset:512
	global_store_dwordx4 v[40:41], v[18:21], off offset:528
	s_cbranch_execnz .LBB0_2023

; DI float bperm(float v, int srclane) { return __int_as_float(__builtin_amdgcn_ds_bpermute(srclane << 2, __float_as_int(v))); }
; DI u32x4 pack8(const float (&v)[8]) { u32x4 w; w.x = pk2(v[0], v[1]); w.y = pk2(v[2], v[3]); w.z = pk2(v[4], v[5]); w.w = pk2(v[6], v[7]); return w; }
; DI void row_stats(const float* STAT, int row, int fq, int lane, float& mu, float& rstd) {
;     const f32x4 a = *(const f32x4*)(STAT + (size_t)row * 32 + fq * 8), b = *(const f32x4*)(STAT + (size_t)row * 32 + fq * 8 + 4);
;     float s = (a[0] + a[2]) + (b[0] + b[2]), q = (a[1] + a[3]) + (b[1] + b[3]);
;     s += bperm(s, lane ^ 16); q += bperm(q, lane ^ 16); s += bperm(s, lane ^ 32); q += bperm(q, lane ^ 32);
;     mu = s * (1.0f / 1024.0f); rstd = __builtin_amdgcn_rsqf(fmaxf(q * (1.0f / 1024.0f) - mu * mu, 0.f) + EPS);
;     DI void operator()(const f32x4 (&acc)[2][2][4][2], const pg8::Unit& u, int wr, int wc, int fr, int fq) const {
;     ...
;             for (int m = 0; m < 4; ++m) { const int row = row0 + ai * 128 + m * 16; const size_t off = (size_t)row * DMODEL + col0; float mu, rstd; row_stats(STAT, row, fq, lane, mu, rstd);
; #pragma unroll
;                 for (int bj = 0; bj < 2; ++bj) { float p[8]; unpack8(*(const u32x4*)(XBin + off + bj * 128), p);
;                     const f32x4 g0 = *(const f32x4*)(g + col0 + bj * 128), g1 = *(const f32x4*)(g + col0 + bj * 128 + 4), b0 = *(const f32x4*)(b + col0 + bj * 128), b1 = *(const f32x4*)(b + col0 + bj * 128 + 4);
;                     float o[8];
; #pragma unroll
;                     for (int k = 0; k < 8; ++k) { const float gg = k < 4 ? g0[k & 3] : g1[k & 3], bb = k < 4 ? b0[k & 3] : b1[k & 3]; const float x1 = (p[k] - mu) * rstd * gg + bb; o[k] = x1 * ALPHA + acc[ai][bj][m][k >> 2][k & 3]; }
;                     if (out32) { *(f32x4*)(out32 + off + bj * 128) = (f32x4){o[0], o[1], o[2], o[3]}; *(f32x4*)(out32 + off + bj * 128 + 4) = (f32x4){o[4], o[5], o[6], o[7]}; }
;                     else *(u32x4*)(XBout + off + bj * 128) = pack8(o); }
.LBB0_2023:
	s_nop 0
	v_add_u32_e32 v18, 0xb0, v146
	v_ashrrev_i32_e32 v19, 31, v18
	v_lshlrev_b64 v[20:21], 10, v[18:19]
	v_lshlrev_b64 v[18:19], 7, v[18:19]
	v_lshl_add_u64 v[18:19], s[36:37], 0, v[18:19]
	v_lshl_add_u64 v[22:23], v[144:145], 2, v[18:19]
	s_nop 1
	v_mov_b32_e32 v26, v220
	v_mov_b32_e32 v27, v221
	v_mov_b32_e32 v28, v222
	v_mov_b32_e32 v29, v223
	v_mov_b32_e32 v30, v224
	v_mov_b32_e32 v31, v225
	v_mov_b32_e32 v32, v226
	v_mov_b32_e32 v33, v227
	v_mov_b32_e32 v34, v228
	v_mov_b32_e32 v35, v229
	v_mov_b32_e32 v36, v230
	v_mov_b32_e32 v37, v231
	v_mov_b32_e32 v38, v232
	v_mov_b32_e32 v39, v233
	v_mov_b32_e32 v40, v234
	v_mov_b32_e32 v41, v235
	v_lshl_add_u64 v[24:25], v[20:21], 0, v[148:149]
	global_load_dwordx4 v[18:21], v[22:23], off offset:16
	global_load_dwordx4 v[42:45], v[22:23], off
	s_mov_b32 s2, 0x3a800000
	s_and_b64 vcc, exec, s[18:19]
	s_waitcnt vmcnt(1)
	v_pk_add_f32 v[18:19], v[18:19], v[20:21]
	s_waitcnt vmcnt(0)
	v_pk_add_f32 v[22:23], v[42:43], v[44:45]
	s_nop 0
	v_pk_add_f32 v[18:19], v[22:23], v[18:19]
	ds_bpermute_b32 v20, v163, v18
	ds_bpermute_b32 v21, v163, v19
	s_waitcnt lgkmcnt(0)
	v_pk_add_f32 v[18:19], v[18:19], v[20:21]
	ds_bpermute_b32 v20, v162, v18
	ds_bpermute_b32 v21, v162, v19
	s_waitcnt lgkmcnt(0)
	v_pk_add_f32 v[18:19], v[18:19], v[20:21]
	s_nop 0
	v_pk_mul_f32 v[20:21], v[18:19], s[2:3] op_sel_hi:[1,0]
	s_nop 0
	v_fma_f32 v18, -v20, v20, v21
	v_max_f32_e32 v18, 0, v18
	v_add_f32_e32 v18, 0x3727c5ac, v18
	v_rsq_f32_e32 v22, v18
	v_lshl_add_u64 v[18:19], v[24:25], 1, s[26:27]
	global_load_dwordx4 v[42:45], v[18:19], off
	v_lshl_add_u64 v[24:25], v[24:25], 2, s[28:29]
	s_waitcnt vmcnt(0)
	v_lshlrev_b32_e32 v46, 16, v42
	v_and_b32_e32 v47, 0xffff0000, v42
	v_pk_add_f32 v[46:47], v[46:47], v[20:21] op_sel_hi:[1,0] neg_lo:[0,1] neg_hi:[0,1]
	s_nop 0
	v_pk_mul_f32 v[46:47], v[46:47], v[22:23] op_sel_hi:[1,0]
	s_nop 0
	v_pk_fma_f32 v[30:31], v[30:31], v[46:47], v[38:39]
	s_nop 0
	v_pk_fma_f32 v[14:15], v[30:31], s[86:87], v[14:15] op_sel_hi:[1,0,1]
	v_lshlrev_b32_e32 v30, 16, v43
	v_and_b32_e32 v31, 0xffff0000, v43
	v_pk_add_f32 v[30:31], v[30:31], v[20:21] op_sel_hi:[1,0] neg_lo:[0,1] neg_hi:[0,1]
	s_nop 0
	v_pk_mul_f32 v[30:31], v[30:31], v[22:23] op_sel_hi:[1,0]
	s_nop 0
	v_pk_fma_f32 v[30:31], v[32:33], v[30:31], v[40:41]
	s_nop 0
	v_pk_fma_f32 v[16:17], v[30:31], s[86:87], v[16:17] op_sel_hi:[1,0,1]
	v_lshlrev_b32_e32 v30, 16, v44
	v_and_b32_e32 v31, 0xffff0000, v44
	v_pk_add_f32 v[30:31], v[30:31], v[20:21] op_sel_hi:[1,0] neg_lo:[0,1] neg_hi:[0,1]
	s_nop 0
	v_pk_mul_f32 v[30:31], v[30:31], v[22:23] op_sel_hi:[1,0]
	s_nop 0
	v_pk_fma_f32 v[26:27], v[26:27], v[30:31], v[34:35]
	s_nop 0
	v_pk_fma_f32 v[10:11], v[26:27], s[86:87], v[10:11] op_sel_hi:[1,0,1]
	v_lshlrev_b32_e32 v26, 16, v45
	v_and_b32_e32 v27, 0xffff0000, v45
	v_pk_add_f32 v[26:27], v[26:27], v[20:21] op_sel_hi:[1,0] neg_lo:[0,1] neg_hi:[0,1]
	s_nop 0
	v_pk_mul_f32 v[26:27], v[26:27], v[22:23] op_sel_hi:[1,0]
	s_nop 0
	v_pk_fma_f32 v[26:27], v[28:29], v[26:27], v[36:37]
	s_nop 0
	v_pk_fma_f32 v[12:13], v[26:27], s[86:87], v[12:13] op_sel_hi:[1,0,1]
	s_cbranch_vccnz .LBB0_2045
	global_store_dwordx4 v[24:25], v[14:17], off
	global_store_dwordx4 v[24:25], v[10:13], off offset:16
	s_cbranch_execnz .LBB0_2026

; DI u32x4 pack8(const float (&v)[8]) { u32x4 w; w.x = pk2(v[0], v[1]); w.y = pk2(v[2], v[3]); w.z = pk2(v[4], v[5]); w.w = pk2(v[6], v[7]); return w; }
;     DI void operator()(const f32x4 (&acc)[2][2][4][2], const pg8::Unit& u, int wr, int wc, int fr, int fq) const {
;     ...
;                 for (int bj = 0; bj < 2; ++bj) { float p[8]; unpack8(*(const u32x4*)(XBin + off + bj * 128), p);
;                     const f32x4 g0 = *(const f32x4*)(g + col0 + bj * 128), g1 = *(const f32x4*)(g + col0 + bj * 128 + 4), b0 = *(const f32x4*)(b + col0 + bj * 128), b1 = *(const f32x4*)(b + col0 + bj * 128 + 4);
;                     float o[8];
; #pragma unroll
;                     for (int k = 0; k < 8; ++k) { const float gg = k < 4 ? g0[k & 3] : g1[k & 3], bb = k < 4 ? b0[k & 3] : b1[k & 3]; const float x1 = (p[k] - mu) * rstd * gg + bb; o[k] = x1 * ALPHA + acc[ai][bj][m][k >> 2][k & 3]; }
;                     if (out32) { *(f32x4*)(out32 + off + bj * 128) = (f32x4){o[0], o[1], o[2], o[3]}; *(f32x4*)(out32 + off + bj * 128 + 4) = (f32x4){o[4], o[5], o[6], o[7]}; }
;                     else *(u32x4*)(XBout + off + bj * 128) = pack8(o); }
.LBB0_2026:
	global_load_dwordx4 v[10:13], v[18:19], off offset:256
	s_nop 0
	s_nop 1
	v_mov_b32_e32 v14, v242
	v_mov_b32_e32 v15, v243
	v_mov_b32_e32 v16, v244
	v_mov_b32_e32 v17, v245
	v_mov_b32_e32 v26, v246
	v_mov_b32_e32 v27, v247
	v_mov_b32_e32 v28, v248
	v_mov_b32_e32 v29, v249
	v_mov_b32_e32 v30, v250
	v_mov_b32_e32 v31, v251
	v_mov_b32_e32 v32, v252
	v_mov_b32_e32 v33, v253
	v_mov_b32_e32 v34, v186
	v_mov_b32_e32 v35, v187
	v_mov_b32_e32 v36, v196
	v_mov_b32_e32 v37, v197
	v_mov_b32_e32 v21, v20
	v_mov_b32_e32 v23, v22
	s_and_b64 vcc, exec, s[18:19]
	s_waitcnt vmcnt(0)
	v_lshlrev_b32_e32 v38, 16, v10
	v_and_b32_e32 v39, 0xffff0000, v10
	v_lshlrev_b32_e32 v10, 16, v11
	v_and_b32_e32 v11, 0xffff0000, v11
	v_pk_add_f32 v[10:11], v[10:11], v[20:21] neg_lo:[0,1] neg_hi:[0,1]
	v_pk_add_f32 v[38:39], v[38:39], v[20:21] neg_lo:[0,1] neg_hi:[0,1]
	v_pk_mul_f32 v[10:11], v[22:23], v[10:11]
	v_pk_mul_f32 v[38:39], v[22:23], v[38:39]
	s_waitcnt vmcnt(0)
	v_pk_fma_f32 v[10:11], v[28:29], v[10:11], v[36:37]
	v_pk_fma_f32 v[26:27], v[26:27], v[38:39], v[34:35]
	v_pk_fma_f32 v[8:9], v[10:11], s[86:87], v[8:9] op_sel_hi:[1,0,1]
	v_lshlrev_b32_e32 v10, 16, v12
	v_and_b32_e32 v11, 0xffff0000, v12
	v_pk_add_f32 v[10:11], v[10:11], v[20:21] neg_lo:[0,1] neg_hi:[0,1]
	v_pk_fma_f32 v[6:7], v[26:27], s[86:87], v[6:7] op_sel_hi:[1,0,1]
	v_pk_mul_f32 v[10:11], v[22:23], v[10:11]
	s_nop 0
	v_pk_fma_f32 v[10:11], v[14:15], v[10:11], v[30:31]
	s_nop 0
	v_pk_fma_f32 v[2:3], v[10:11], s[86:87], v[2:3] op_sel_hi:[1,0,1]
	v_lshlrev_b32_e32 v10, 16, v13
	v_and_b32_e32 v11, 0xffff0000, v13
	v_pk_add_f32 v[10:11], v[10:11], v[20:21] neg_lo:[0,1] neg_hi:[0,1]
	s_nop 0
	v_pk_mul_f32 v[10:11], v[22:23], v[10:11]
	s_nop 0
	v_pk_fma_f32 v[10:11], v[16:17], v[10:11], v[32:33]
	s_nop 0
	v_pk_fma_f32 v[4:5], v[10:11], s[86:87], v[4:5] op_sel_hi:[1,0,1]
	s_cbranch_vccnz .LBB0_2046
	global_store_dwordx4 v[24:25], v[6:9], off offset:512
	global_store_dwordx4 v[24:25], v[2:5], off offset:528
	s_cbranch_execnz .LBB0_2029
